# nt (non-temporal) hint on the read-once f32 input loads: P0 x rows / weight transposes / mem rows and P3 deferred weight conversions (keeps the infinity cache for PROJ/KVC/ST); on top of v8
# speedup vs baseline: 1.0438x; 1.0337x over previous
; #define LAS __attribute__((address_space(3)))
; #define LDS_WAIT() asm volatile("s_waitcnt lgkmcnt(0)" ::: "memory")
; __device__ __forceinline__ unsigned pk2(float lo, float hi) { return pg8::cvt_pk_bf16(lo, hi); }
; __device__ __forceinline__ void wt_store16(const WsRef& w, const void* p, u32x4 v) { __builtin_amdgcn_raw_buffer_store_b128(v, w.r, (unsigned)((const unsigned char*)p - w.base), 0, 16); }
; __device__ __forceinline__ void p0_transpose_item64(const WsRef& wsr, const float* W, int K, int N, bf16* WT, LAS float* scr, int item, int lane, const float* kscale = nullptr) {
;     const int nblk = N / 64, kb = item / nblk, nb = item % nblk, k0 = 64 * kb, n0 = 64 * nb;
;     const int kq = lane >> 4, nq = lane & 15;
;     f32x4 v[16];
; #pragma unroll
;     for (int i = 0; i < 16; ++i) v[i] = *(const f32x4*)(W + (size_t)(k0 + 4 * i + kq) * N + n0 + nq * 4);
; #pragma unroll
;     for (int i = 0; i < 16; ++i) { const int kk = 4 * i + kq; const float sc = kscale ? kscale[k0 + kk] : 1.0f; LAS float* d = scr + kk * 65 + nq * 4;
;         d[0] = v[i][0] * sc; d[1] = v[i][1] * sc; d[2] = v[i][2] * sc; d[3] = v[i][3] * sc; }
;     LDS_WAIT(); asm volatile("" ::: "memory");
;     const int c = lane & 7;
; #pragma unroll
;     for (int j = 0; j < 8; ++j) { const int n = (lane >> 3) + 8 * j; const LAS float* s = scr + (8 * c) * 65 + n;
;         u32x4 o; o.x = pk2(s[0 * 65], s[1 * 65]); o.y = pk2(s[2 * 65], s[3 * 65]); o.z = pk2(s[4 * 65], s[5 * 65]); o.w = pk2(s[6 * 65], s[7 * 65]);
;         wt_store16(wsr, WT + (size_t)(n0 + n) * K + k0 + 8 * c, o); }
;     LDS_WAIT(); asm volatile("" ::: "memory");
; }
; __global__ void __launch_bounds__(512, 2) fwd_mega(Args a) {
;     ...
;             if (r < I_IN) { p0_transpose_item64(wsr, a.in[4], D, INC, WIN, scr, r, lane, a.in[3]); continue; } r -= I_IN;
;             p0_transpose_item64(wsr, a.in[17], D, 2 * D, WXKV, scr, r, lane); }
.LBB0_22:
	s_mov_b64 s[0:1], -1
	s_cmpk_gt_i32 s55, 0x2ff
	v_add_u32_e32 v117, 0x400, v71
	s_cbranch_scc0 .LBB0_24
	s_and_b32 s1, s52, 0x1ffc0
	s_and_b32 s0, s3, 0x7c0
	v_or_b32_e32 v2, s1, v64
	s_lshl_b32 s6, s0, 2
	v_lshl_add_u64 v[0:1], v[68:69], 0, s[6:7]
	v_lshlrev_b32_e32 v66, 13, v2
	v_lshl_add_u64 v[60:61], v[0:1], 0, v[66:67]
	v_add_co_u32_e32 v4, vcc, 0x8000, v60
	s_mov_b32 s88, s84
	s_nop 0
	v_addc_co_u32_e32 v5, vcc, 0, v61, vcc
	v_add_co_u32_e32 v8, vcc, 0x10000, v60
	global_load_dwordx4 v[0:3], v[60:61], off nt
	s_nop 0
	global_load_dwordx4 v[4:7], v[4:5], off nt
	v_addc_co_u32_e32 v9, vcc, 0, v61, vcc
	v_add_co_u32_e32 v12, vcc, 0x18000, v60
	s_nop 1
	v_addc_co_u32_e32 v13, vcc, 0, v61, vcc
	v_add_co_u32_e32 v16, vcc, 0x20000, v60
	global_load_dwordx4 v[8:11], v[8:9], off nt
	s_nop 0
	global_load_dwordx4 v[12:15], v[12:13], off nt
	v_addc_co_u32_e32 v17, vcc, 0, v61, vcc
	v_add_co_u32_e32 v20, vcc, 0x28000, v60
	s_nop 1
	v_addc_co_u32_e32 v21, vcc, 0, v61, vcc
	v_add_co_u32_e32 v24, vcc, 0x30000, v60
	global_load_dwordx4 v[16:19], v[16:17], off nt
	s_nop 0
	global_load_dwordx4 v[20:23], v[20:21], off nt
	v_addc_co_u32_e32 v25, vcc, 0, v61, vcc
	v_add_co_u32_e32 v28, vcc, 0x38000, v60
	s_nop 1
	v_addc_co_u32_e32 v29, vcc, 0, v61, vcc
	v_add_co_u32_e32 v32, vcc, 0x40000, v60
	global_load_dwordx4 v[24:27], v[24:25], off nt
	s_nop 0
	global_load_dwordx4 v[28:31], v[28:29], off nt
	v_addc_co_u32_e32 v33, vcc, 0, v61, vcc
	v_add_co_u32_e32 v36, vcc, 0x48000, v60
	s_nop 1
	v_addc_co_u32_e32 v37, vcc, 0, v61, vcc
	v_add_co_u32_e32 v40, vcc, 0x50000, v60
	global_load_dwordx4 v[32:35], v[32:33], off nt
	s_nop 0
	global_load_dwordx4 v[36:39], v[36:37], off nt
	v_addc_co_u32_e32 v41, vcc, 0, v61, vcc
	v_add_co_u32_e32 v44, vcc, 0x58000, v60
	s_nop 1
	v_addc_co_u32_e32 v45, vcc, 0, v61, vcc
	v_add_co_u32_e32 v48, vcc, 0x60000, v60
	global_load_dwordx4 v[40:43], v[40:41], off nt
	s_nop 0
	global_load_dwordx4 v[44:47], v[44:45], off nt
	v_addc_co_u32_e32 v49, vcc, 0, v61, vcc
	v_add_co_u32_e32 v52, vcc, 0x68000, v60
	s_nop 1
	v_addc_co_u32_e32 v53, vcc, 0, v61, vcc
	v_add_co_u32_e32 v56, vcc, 0x70000, v60
	global_load_dwordx4 v[48:51], v[48:49], off nt
	s_nop 0
	global_load_dwordx4 v[52:55], v[52:53], off nt
	v_addc_co_u32_e32 v57, vcc, 0, v61, vcc
	v_add_co_u32_e32 v60, vcc, 0x78000, v60
	global_load_dwordx4 v[56:59], v[56:57], off nt
	s_nop 0
	v_addc_co_u32_e32 v61, vcc, 0, v61, vcc
	global_load_dwordx4 v[60:63], v[60:61], off nt
	s_waitcnt vmcnt(15)
	ds_write2_b32 v75, v0, v1 offset1:1
	ds_write2_b32 v75, v2, v3 offset0:2 offset1:3
	s_waitcnt vmcnt(14)
	ds_write2_b32 v86, v4, v5 offset1:1
	ds_write2_b32 v87, v6, v7 offset1:1
	s_waitcnt vmcnt(13)
	ds_write2_b32 v88, v8, v9 offset1:1
	ds_write2_b32 v89, v10, v11 offset1:1
	s_waitcnt vmcnt(12)
	ds_write2_b32 v90, v12, v13 offset1:1
	ds_write2_b32 v91, v14, v15 offset1:1
	s_waitcnt vmcnt(11)
	ds_write2_b32 v92, v16, v17 offset1:1
	ds_write2_b32 v93, v18, v19 offset1:1
	s_waitcnt vmcnt(10)
	ds_write2_b32 v94, v20, v21 offset1:1
	ds_write2_b32 v95, v22, v23 offset1:1
	s_waitcnt vmcnt(9)
	ds_write2_b32 v96, v24, v25 offset1:1
	ds_write2_b32 v97, v26, v27 offset1:1
	s_waitcnt vmcnt(8)
	ds_write2_b32 v98, v28, v29 offset1:1
	ds_write2_b32 v99, v30, v31 offset1:1
	s_waitcnt vmcnt(7)
	ds_write2_b32 v100, v32, v33 offset1:1
	ds_write2_b32 v101, v34, v35 offset1:1
	s_waitcnt vmcnt(6)
	ds_write2_b32 v102, v36, v37 offset1:1
	ds_write2_b32 v103, v38, v39 offset1:1
	s_waitcnt vmcnt(5)
	ds_write2_b32 v104, v40, v41 offset1:1
	ds_write2_b32 v105, v42, v43 offset1:1
	s_waitcnt vmcnt(4)
	ds_write2_b32 v106, v44, v45 offset1:1
	ds_write2_b32 v107, v46, v47 offset1:1
	s_waitcnt vmcnt(3)
	ds_write2_b32 v108, v48, v49 offset1:1
	ds_write2_b32 v109, v50, v51 offset1:1
	s_waitcnt vmcnt(2)
	ds_write2_b32 v112, v52, v53 offset1:1
	ds_write2_b32 v113, v54, v55 offset1:1
	s_waitcnt vmcnt(1)
	ds_write2_b32 v114, v56, v57 offset1:1
	v_add_u32_e32 v0, 0x38e8, v75
	v_lshl_add_u32 v20, s1, 1, v70
	ds_write2_b32 v0, v58, v59 offset1:1
	v_add_u32_e32 v0, 0x3cf0, v75
	s_waitcnt vmcnt(0)
	ds_write2_b32 v0, v60, v61 offset1:1
	v_add_u32_e32 v0, 0x3cf8, v75
	ds_write2_b32 v0, v62, v63 offset1:1
	s_waitcnt lgkmcnt(0)
	ds_read2_b32 v[4:5], v71 offset1:8
	ds_read2_b32 v[6:7], v71 offset0:65 offset1:73
	ds_read2_b32 v[8:9], v71 offset0:130 offset1:138
	ds_read2_b32 v[10:11], v71 offset0:195 offset1:203
	ds_read2_b32 v[12:13], v117 offset0:4 offset1:12
	ds_read2_b32 v[14:15], v117 offset0:69 offset1:77
	ds_read2_b32 v[16:17], v117 offset0:134 offset1:142
	ds_read2_b32 v[18:19], v117 offset0:199 offset1:207
	s_waitcnt lgkmcnt(6)
	v_cvt_pk_bf16_f32 v0, v4, v6
	v_or_b32_e32 v4, s0, v78
	v_lshl_add_u32 v4, v4, 11, v20
	s_waitcnt lgkmcnt(4)
	v_cvt_pk_bf16_f32 v1, v8, v10
	s_waitcnt lgkmcnt(2)
	v_cvt_pk_bf16_f32 v2, v12, v14
	s_waitcnt lgkmcnt(0)
	v_cvt_pk_bf16_f32 v3, v16, v18
	v_subrev_u32_e32 v4, s84, v4
	buffer_store_dwordx4 v[0:3], v4, s[88:91], 0 offen sc1
	v_or_b32_e32 v4, s0, v79
	v_lshl_add_u32 v4, v4, 11, v20
	v_cvt_pk_bf16_f32 v0, v5, v7
	v_cvt_pk_bf16_f32 v1, v9, v11
	v_cvt_pk_bf16_f32 v2, v13, v15
	v_cvt_pk_bf16_f32 v3, v17, v19
	v_subrev_u32_e32 v21, s84, v4
	ds_read2_b32 v[4:5], v71 offset0:16 offset1:24
	ds_read2_b32 v[6:7], v71 offset0:81 offset1:89
	ds_read2_b32 v[8:9], v71 offset0:146 offset1:154
	ds_read2_b32 v[10:11], v71 offset0:211 offset1:219
	ds_read2_b32 v[12:13], v117 offset0:20 offset1:28
	ds_read2_b32 v[14:15], v117 offset0:85 offset1:93
	ds_read2_b32 v[16:17], v117 offset0:150 offset1:158
	ds_read2_b32 v[18:19], v117 offset0:215 offset1:223
	buffer_store_dwordx4 v[0:3], v21, s[88:91], 0 offen sc1
	s_waitcnt lgkmcnt(6)
; #define LAS __attribute__((address_space(3)))
; __device__ __forceinline__ void p0_transpose_item64(const WsRef& wsr, const float* W, int K, int N, bf16* WT, LAS float* scr, int item, int lane, const float* kscale = nullptr) {
;     const int nblk = N / 64, kb = item / nblk, nb = item % nblk, k0 = 64 * kb, n0 = 64 * nb;
;     const int kq = lane >> 4, nq = lane & 15;
;     f32x4 v[16];
; #pragma unroll
;     for (int i = 0; i < 16; ++i) v[i] = *(const f32x4*)(W + (size_t)(k0 + 4 * i + kq) * N + n0 + nq * 4);
; #pragma unroll
;     for (int i = 0; i < 16; ++i) { const int kk = 4 * i + kq; const float sc = kscale ? kscale[k0 + kk] : 1.0f; LAS float* d = scr + kk * 65 + nq * 4;
;         d[0] = v[i][0] * sc; d[1] = v[i][1] * sc; d[2] = v[i][2] * sc; d[3] = v[i][3] * sc; }
	s_nop 0
	v_cvt_pk_bf16_f32 v0, v4, v6
	v_or_b32_e32 v4, s0, v80
	v_lshl_add_u32 v4, v4, 11, v20
	s_waitcnt lgkmcnt(4)
	v_cvt_pk_bf16_f32 v1, v8, v10
	s_waitcnt lgkmcnt(2)
	v_cvt_pk_bf16_f32 v2, v12, v14
	s_waitcnt lgkmcnt(0)
	v_cvt_pk_bf16_f32 v3, v16, v18
	v_subrev_u32_e32 v4, s84, v4
	buffer_store_dwordx4 v[0:3], v4, s[88:91], 0 offen sc1
	v_or_b32_e32 v4, s0, v81
	v_lshl_add_u32 v4, v4, 11, v20
	v_cvt_pk_bf16_f32 v0, v5, v7
	v_cvt_pk_bf16_f32 v1, v9, v11
	v_cvt_pk_bf16_f32 v2, v13, v15
	v_cvt_pk_bf16_f32 v3, v17, v19
	v_subrev_u32_e32 v21, s84, v4
	ds_read2_b32 v[4:5], v71 offset0:32 offset1:40
	ds_read2_b32 v[6:7], v71 offset0:97 offset1:105
	ds_read2_b32 v[8:9], v71 offset0:162 offset1:170
	ds_read2_b32 v[10:11], v71 offset0:227 offset1:235
	ds_read2_b32 v[12:13], v117 offset0:36 offset1:44
	ds_read2_b32 v[14:15], v117 offset0:101 offset1:109
	ds_read2_b32 v[16:17], v117 offset0:166 offset1:174
	ds_read2_b32 v[18:19], v117 offset0:231 offset1:239
	buffer_store_dwordx4 v[0:3], v21, s[88:91], 0 offen sc1
	s_waitcnt lgkmcnt(6)
	s_nop 0
	v_cvt_pk_bf16_f32 v0, v4, v6
	v_or_b32_e32 v4, s0, v82
	v_lshl_add_u32 v4, v4, 11, v20
	s_waitcnt lgkmcnt(4)
	v_cvt_pk_bf16_f32 v1, v8, v10
	s_waitcnt lgkmcnt(2)
	v_cvt_pk_bf16_f32 v2, v12, v14
	s_waitcnt lgkmcnt(0)
	v_cvt_pk_bf16_f32 v3, v16, v18
	v_subrev_u32_e32 v4, s84, v4
	buffer_store_dwordx4 v[0:3], v4, s[88:91], 0 offen sc1
	v_or_b32_e32 v4, s0, v83
	v_lshl_add_u32 v4, v4, 11, v20
	v_cvt_pk_bf16_f32 v0, v5, v7
	v_cvt_pk_bf16_f32 v1, v9, v11
	v_cvt_pk_bf16_f32 v2, v13, v15
	v_cvt_pk_bf16_f32 v3, v17, v19
	v_subrev_u32_e32 v21, s84, v4
	ds_read2_b32 v[4:5], v71 offset0:48 offset1:56
	ds_read2_b32 v[6:7], v71 offset0:113 offset1:121
	ds_read2_b32 v[8:9], v71 offset0:178 offset1:186
	ds_read2_b32 v[10:11], v71 offset0:243 offset1:251
	ds_read2_b32 v[12:13], v117 offset0:52 offset1:60
	ds_read2_b32 v[14:15], v117 offset0:117 offset1:125
	ds_read2_b32 v[16:17], v117 offset0:182 offset1:190
	ds_read2_b32 v[18:19], v117 offset0:247 offset1:255
	buffer_store_dwordx4 v[0:3], v21, s[88:91], 0 offen sc1
	s_waitcnt lgkmcnt(6)
	s_nop 0
	v_cvt_pk_bf16_f32 v0, v4, v6
	v_or_b32_e32 v4, s0, v84
	v_lshl_add_u32 v4, v4, 11, v20
	s_waitcnt lgkmcnt(4)
	v_cvt_pk_bf16_f32 v1, v8, v10
	s_waitcnt lgkmcnt(2)
	v_cvt_pk_bf16_f32 v2, v12, v14
	s_waitcnt lgkmcnt(0)
	v_cvt_pk_bf16_f32 v3, v16, v18
	v_subrev_u32_e32 v4, s84, v4
	buffer_store_dwordx4 v[0:3], v4, s[88:91], 0 offen sc1
	v_or_b32_e32 v4, s0, v85
	v_lshl_add_u32 v4, v4, 11, v20
	v_cvt_pk_bf16_f32 v0, v5, v7
	v_cvt_pk_bf16_f32 v1, v9, v11
	v_cvt_pk_bf16_f32 v2, v13, v15
	v_cvt_pk_bf16_f32 v3, v17, v19
	v_subrev_u32_e32 v4, s84, v4
	buffer_store_dwordx4 v[0:3], v4, s[88:91], 0 offen sc1
	s_waitcnt lgkmcnt(0)
	s_mov_b64 s[0:1], 0
.LBB0_24:
	s_andn2_b64 vcc, exec, s[0:1]
	s_cbranch_vccnz .LBB0_21
	s_mul_hi_i32 s0, s55, 0x2aaaaaab
	s_lshr_b32 s1, s0, 31
	s_ashr_i32 s0, s0, 3
	s_add_i32 s0, s0, s1
	s_lshl_b32 s34, s0, 6
	s_mulk_i32 s0, 0xf400
	s_add_i32 s30, s3, s0
	v_or_b32_e32 v76, s34, v64
	s_ashr_i32 s31, s30, 31
	v_lshl_add_u64 v[0:1], s[30:31], 2, v[72:73]
	v_or_b32_e32 v4, 4, v76
	v_mad_i64_i32 v[2:3], s[0:1], v76, s54, v[0:1]
	v_mad_i64_i32 v[4:5], s[0:1], v4, s54, v[0:1]
	global_load_dwordx4 v[60:63], v[2:3], off nt
	global_load_dwordx4 v[56:59], v[4:5], off nt
	v_or_b32_e32 v2, 8, v76
	v_or_b32_e32 v4, 12, v76
	v_mad_i64_i32 v[2:3], s[0:1], v2, s54, v[0:1]
	v_mad_i64_i32 v[4:5], s[0:1], v4, s54, v[0:1]
	global_load_dwordx4 v[52:55], v[2:3], off nt
	global_load_dwordx4 v[48:51], v[4:5], off nt
	v_or_b32_e32 v2, 16, v76
	v_or_b32_e32 v4, 20, v76
	v_mad_i64_i32 v[2:3], s[0:1], v2, s54, v[0:1]
	v_mad_i64_i32 v[4:5], s[0:1], v4, s54, v[0:1]
	global_load_dwordx4 v[44:47], v[2:3], off nt
	global_load_dwordx4 v[40:43], v[4:5], off nt
	v_or_b32_e32 v2, 24, v76
	v_or_b32_e32 v4, 28, v76
	v_mad_i64_i32 v[2:3], s[0:1], v2, s54, v[0:1]
	v_mad_i64_i32 v[4:5], s[0:1], v4, s54, v[0:1]
	global_load_dwordx4 v[36:39], v[2:3], off nt
	global_load_dwordx4 v[32:35], v[4:5], off nt
	v_or_b32_e32 v2, 32, v76
	v_or_b32_e32 v4, 36, v76
	v_mad_i64_i32 v[2:3], s[0:1], v2, s54, v[0:1]
	v_mad_i64_i32 v[4:5], s[0:1], v4, s54, v[0:1]
	v_or_b32_e32 v10, 56, v76
	global_load_dwordx4 v[28:31], v[2:3], off nt
	global_load_dwordx4 v[24:27], v[4:5], off nt
	v_or_b32_e32 v2, 40, v76
	v_or_b32_e32 v4, 44, v76
	v_or_b32_e32 v6, 48, v76
	v_or_b32_e32 v8, 52, v76
	v_mad_i64_i32 v[118:119], s[0:1], v10, s54, v[0:1]
	v_or_b32_e32 v10, 60, v76
	v_mad_i64_i32 v[2:3], s[0:1], v2, s54, v[0:1]
	v_mad_i64_i32 v[4:5], s[0:1], v4, s54, v[0:1]
	v_mad_i64_i32 v[6:7], s[0:1], v6, s54, v[0:1]
	v_mad_i64_i32 v[8:9], s[0:1], v8, s54, v[0:1]
	v_mad_i64_i32 v[0:1], s[0:1], v10, s54, v[0:1]
	global_load_dwordx4 v[20:23], v[2:3], off nt
	global_load_dwordx4 v[16:19], v[4:5], off nt
	global_load_dwordx4 v[12:15], v[6:7], off nt
	s_nop 0
	global_load_dwordx4 v[8:11], v[8:9], off nt
	s_nop 0
	global_load_dwordx4 v[4:7], v[118:119], off nt
	s_nop 0
	global_load_dwordx4 v[0:3], v[0:1], off nt
	v_cndmask_b32_e64 v66, 0, 1, s[16:17]
	v_cmp_ne_u32_e64 s[0:1], 1, v66
	s_andn2_b64 vcc, exec, s[16:17]
	s_cbranch_vccnz .LBB0_48
	v_ashrrev_i32_e32 v77, 31, v76
	s_ashr_i32 s35, s34, 31
	v_lshl_add_u64 v[76:77], v[76:77], 2, s[14:15]
	v_lshl_add_u64 v[118:119], s[34:35], 0, v[64:65]
	global_load_dword v76, v[76:77], off nt
	v_lshl_add_u64 v[118:119], v[118:119], 2, s[14:15]
	global_load_dword v66, v[118:119], off offset:16 nt
	s_waitcnt vmcnt(1)
	v_pk_mul_f32 v[118:119], v[60:61], v[76:77] op_sel_hi:[1,0]
	v_pk_mul_f32 v[76:77], v[62:63], v[76:77] op_sel_hi:[1,0]
	ds_write2_b32 v75, v118, v119 offset1:1
	ds_write2_b32 v75, v76, v77 offset0:2 offset1:3
	s_cbranch_execnz .LBB0_28

; #define LAS __attribute__((address_space(3)))
; __device__ __forceinline__ void p0_transpose_item64(const WsRef& wsr, const float* W, int K, int N, bf16* WT, LAS float* scr, int item, int lane, const float* kscale = nullptr) {
;     ...
;     for (int i = 0; i < 16; ++i) v[i] = *(const f32x4*)(W + (size_t)(k0 + 4 * i + kq) * N + n0 + nq * 4);
; #pragma unroll
;     for (int i = 0; i < 16; ++i) { const int kk = 4 * i + kq; const float sc = kscale ? kscale[k0 + kk] : 1.0f; LAS float* d = scr + kk * 65 + nq * 4;
;         d[0] = v[i][0] * sc; d[1] = v[i][1] * sc; d[2] = v[i][2] * sc; d[3] = v[i][3] * sc; }
.LBB0_28:
	s_waitcnt vmcnt(0)
	v_pk_mul_f32 v[56:57], v[56:57], v[66:67] op_sel_hi:[1,0]
	ds_write2_b32 v110, v56, v57 offset1:1
	v_pk_mul_f32 v[56:57], v[58:59], v[66:67] op_sel_hi:[1,0]
	s_and_b64 vcc, exec, s[0:1]
	ds_write2_b32 v110, v56, v57 offset0:2 offset1:3
	s_cbranch_vccnz .LBB0_49
	s_ashr_i32 s35, s34, 31
	v_lshl_add_u64 v[56:57], s[34:35], 0, v[64:65]
	v_lshl_add_u64 v[56:57], v[56:57], 2, s[14:15]
	global_load_dword v58, v[56:57], off offset:32 nt
	s_nop 0
	global_load_dword v56, v[56:57], off offset:48 nt
	s_waitcnt vmcnt(1)
	v_pk_mul_f32 v[60:61], v[52:53], v[58:59] op_sel_hi:[1,0]
	v_pk_mul_f32 v[58:59], v[54:55], v[58:59] op_sel_hi:[1,0]
	ds_write2_b32 v115, v60, v61 offset1:1
	ds_write2_b32 v115, v58, v59 offset0:2 offset1:3
	s_cbranch_execnz .LBB0_31

; #define LAS __attribute__((address_space(3)))
; __device__ __forceinline__ void p0_transpose_item64(const WsRef& wsr, const float* W, int K, int N, bf16* WT, LAS float* scr, int item, int lane, const float* kscale = nullptr) {
;     ...
;     for (int i = 0; i < 16; ++i) v[i] = *(const f32x4*)(W + (size_t)(k0 + 4 * i + kq) * N + n0 + nq * 4);
; #pragma unroll
;     for (int i = 0; i < 16; ++i) { const int kk = 4 * i + kq; const float sc = kscale ? kscale[k0 + kk] : 1.0f; LAS float* d = scr + kk * 65 + nq * 4;
;         d[0] = v[i][0] * sc; d[1] = v[i][1] * sc; d[2] = v[i][2] * sc; d[3] = v[i][3] * sc; }
.LBB0_31:
	s_waitcnt vmcnt(0)
	v_pk_mul_f32 v[48:49], v[48:49], v[56:57] op_sel_hi:[1,0]
	ds_write2_b32 v111, v48, v49 offset1:1
	v_pk_mul_f32 v[48:49], v[50:51], v[56:57] op_sel_hi:[1,0]
	s_and_b64 vcc, exec, s[0:1]
	ds_write2_b32 v111, v48, v49 offset0:2 offset1:3
	s_cbranch_vccnz .LBB0_50
	s_ashr_i32 s35, s34, 31
	v_lshl_add_u64 v[48:49], s[34:35], 0, v[64:65]
	v_lshl_add_u64 v[48:49], v[48:49], 2, s[14:15]
	global_load_dword v50, v[48:49], off offset:64 nt
	s_nop 0
	global_load_dword v48, v[48:49], off offset:80 nt
	s_waitcnt vmcnt(1)
	v_pk_mul_f32 v[52:53], v[44:45], v[50:51] op_sel_hi:[1,0]
	v_pk_mul_f32 v[50:51], v[46:47], v[50:51] op_sel_hi:[1,0]
	ds_write2_b32 v116, v52, v53 offset1:1
	ds_write2_b32 v116, v50, v51 offset0:2 offset1:3
	s_cbranch_execnz .LBB0_34

; #define LAS __attribute__((address_space(3)))
; __device__ __forceinline__ void p0_transpose_item64(const WsRef& wsr, const float* W, int K, int N, bf16* WT, LAS float* scr, int item, int lane, const float* kscale = nullptr) {
;     ...
;     for (int i = 0; i < 16; ++i) v[i] = *(const f32x4*)(W + (size_t)(k0 + 4 * i + kq) * N + n0 + nq * 4);
; #pragma unroll
;     for (int i = 0; i < 16; ++i) { const int kk = 4 * i + kq; const float sc = kscale ? kscale[k0 + kk] : 1.0f; LAS float* d = scr + kk * 65 + nq * 4;
;         d[0] = v[i][0] * sc; d[1] = v[i][1] * sc; d[2] = v[i][2] * sc; d[3] = v[i][3] * sc; }
.LBB0_34:
	s_waitcnt vmcnt(0)
	v_pk_mul_f32 v[40:41], v[40:41], v[48:49] op_sel_hi:[1,0]
	v_add_u32_e32 v44, 0x410, v116
	ds_write2_b32 v44, v40, v41 offset1:1
	v_pk_mul_f32 v[40:41], v[42:43], v[48:49] op_sel_hi:[1,0]
	v_add_u32_e32 v42, 0x418, v116
	ds_write2_b32 v42, v40, v41 offset1:1
	s_and_b64 vcc, exec, s[0:1]
	v_add_u32_e32 v41, 0x820, v116
	v_add_u32_e32 v42, 0x828, v116
	s_cbranch_vccnz .LBB0_51
	s_ashr_i32 s35, s34, 31
	v_lshl_add_u64 v[44:45], s[34:35], 0, v[64:65]
	v_lshl_add_u64 v[44:45], v[44:45], 2, s[14:15]
	global_load_dword v46, v[44:45], off offset:96 nt
	global_load_dword v40, v[44:45], off offset:112 nt
	s_waitcnt vmcnt(1)
	v_pk_mul_f32 v[44:45], v[36:37], v[46:47] op_sel_hi:[1,0]
	v_pk_mul_f32 v[46:47], v[38:39], v[46:47] op_sel_hi:[1,0]
	ds_write2_b32 v41, v44, v45 offset1:1
	ds_write2_b32 v42, v46, v47 offset1:1
	s_cbranch_execnz .LBB0_37

; #define LAS __attribute__((address_space(3)))
; __device__ __forceinline__ void p0_transpose_item64(const WsRef& wsr, const float* W, int K, int N, bf16* WT, LAS float* scr, int item, int lane, const float* kscale = nullptr) {
;     ...
;     for (int i = 0; i < 16; ++i) v[i] = *(const f32x4*)(W + (size_t)(k0 + 4 * i + kq) * N + n0 + nq * 4);
; #pragma unroll
;     for (int i = 0; i < 16; ++i) { const int kk = 4 * i + kq; const float sc = kscale ? kscale[k0 + kk] : 1.0f; LAS float* d = scr + kk * 65 + nq * 4;
;         d[0] = v[i][0] * sc; d[1] = v[i][1] * sc; d[2] = v[i][2] * sc; d[3] = v[i][3] * sc; }
.LBB0_37:
	s_waitcnt vmcnt(0)
	v_pk_mul_f32 v[32:33], v[32:33], v[40:41] op_sel_hi:[1,0]
	v_add_u32_e32 v36, 0xc30, v116
	ds_write2_b32 v36, v32, v33 offset1:1
	v_pk_mul_f32 v[32:33], v[34:35], v[40:41] op_sel_hi:[1,0]
	v_add_u32_e32 v34, 0xc38, v116
	ds_write2_b32 v34, v32, v33 offset1:1
	s_and_b64 vcc, exec, s[0:1]
	v_add_u32_e32 v33, 0x1040, v116
	v_add_u32_e32 v34, 0x1048, v116
	s_cbranch_vccnz .LBB0_52
	s_ashr_i32 s35, s34, 31
	v_lshl_add_u64 v[36:37], s[34:35], 0, v[64:65]
	v_lshl_add_u64 v[36:37], v[36:37], 2, s[14:15]
	global_load_dword v38, v[36:37], off offset:128 nt
	global_load_dword v32, v[36:37], off offset:144 nt
	s_waitcnt vmcnt(1)
	v_pk_mul_f32 v[36:37], v[28:29], v[38:39] op_sel_hi:[1,0]
	v_pk_mul_f32 v[38:39], v[30:31], v[38:39] op_sel_hi:[1,0]
	ds_write2_b32 v33, v36, v37 offset1:1
	ds_write2_b32 v34, v38, v39 offset1:1
	s_cbranch_execnz .LBB0_40

; #define LAS __attribute__((address_space(3)))
; __device__ __forceinline__ void p0_transpose_item64(const WsRef& wsr, const float* W, int K, int N, bf16* WT, LAS float* scr, int item, int lane, const float* kscale = nullptr) {
;     ...
;     for (int i = 0; i < 16; ++i) v[i] = *(const f32x4*)(W + (size_t)(k0 + 4 * i + kq) * N + n0 + nq * 4);
; #pragma unroll
;     for (int i = 0; i < 16; ++i) { const int kk = 4 * i + kq; const float sc = kscale ? kscale[k0 + kk] : 1.0f; LAS float* d = scr + kk * 65 + nq * 4;
;         d[0] = v[i][0] * sc; d[1] = v[i][1] * sc; d[2] = v[i][2] * sc; d[3] = v[i][3] * sc; }
.LBB0_40:
	s_waitcnt vmcnt(0)
	v_pk_mul_f32 v[24:25], v[24:25], v[32:33] op_sel_hi:[1,0]
	v_add_u32_e32 v28, 0x1450, v116
	ds_write2_b32 v28, v24, v25 offset1:1
	v_pk_mul_f32 v[24:25], v[26:27], v[32:33] op_sel_hi:[1,0]
	v_add_u32_e32 v26, 0x1458, v116
	ds_write2_b32 v26, v24, v25 offset1:1
	s_and_b64 vcc, exec, s[0:1]
	v_add_u32_e32 v25, 0x1860, v116
	v_add_u32_e32 v26, 0x1868, v116
	s_cbranch_vccnz .LBB0_53
	s_ashr_i32 s35, s34, 31
	v_lshl_add_u64 v[28:29], s[34:35], 0, v[64:65]
	v_lshl_add_u64 v[28:29], v[28:29], 2, s[14:15]
	global_load_dword v30, v[28:29], off offset:160 nt
	global_load_dword v24, v[28:29], off offset:176 nt
	s_waitcnt vmcnt(1)
	v_pk_mul_f32 v[28:29], v[20:21], v[30:31] op_sel_hi:[1,0]
	v_pk_mul_f32 v[30:31], v[22:23], v[30:31] op_sel_hi:[1,0]
	ds_write2_b32 v25, v28, v29 offset1:1
	ds_write2_b32 v26, v30, v31 offset1:1
	s_cbranch_execnz .LBB0_43

; #define LAS __attribute__((address_space(3)))
; __device__ __forceinline__ void p0_transpose_item64(const WsRef& wsr, const float* W, int K, int N, bf16* WT, LAS float* scr, int item, int lane, const float* kscale = nullptr) {
;     ...
;     for (int i = 0; i < 16; ++i) v[i] = *(const f32x4*)(W + (size_t)(k0 + 4 * i + kq) * N + n0 + nq * 4);
; #pragma unroll
;     for (int i = 0; i < 16; ++i) { const int kk = 4 * i + kq; const float sc = kscale ? kscale[k0 + kk] : 1.0f; LAS float* d = scr + kk * 65 + nq * 4;
;         d[0] = v[i][0] * sc; d[1] = v[i][1] * sc; d[2] = v[i][2] * sc; d[3] = v[i][3] * sc; }
.LBB0_43:
	s_waitcnt vmcnt(0)
	v_pk_mul_f32 v[16:17], v[16:17], v[24:25] op_sel_hi:[1,0]
	v_add_u32_e32 v20, 0x1c70, v116
	ds_write2_b32 v20, v16, v17 offset1:1
	v_pk_mul_f32 v[16:17], v[18:19], v[24:25] op_sel_hi:[1,0]
	v_add_u32_e32 v18, 0x1c78, v116
	ds_write2_b32 v18, v16, v17 offset1:1
	s_and_b64 vcc, exec, s[0:1]
	v_add_u32_e32 v17, 0x2080, v116
	v_add_u32_e32 v18, 0x2088, v116
	s_cbranch_vccnz .LBB0_54
	s_ashr_i32 s35, s34, 31
	v_lshl_add_u64 v[20:21], s[34:35], 0, v[64:65]
	v_lshl_add_u64 v[20:21], v[20:21], 2, s[14:15]
	global_load_dword v22, v[20:21], off offset:192 nt
	global_load_dword v16, v[20:21], off offset:208 nt
	s_waitcnt vmcnt(1)
	v_pk_mul_f32 v[20:21], v[12:13], v[22:23] op_sel_hi:[1,0]
	v_pk_mul_f32 v[22:23], v[14:15], v[22:23] op_sel_hi:[1,0]
	ds_write2_b32 v17, v20, v21 offset1:1
	ds_write2_b32 v18, v22, v23 offset1:1
	s_cbranch_execnz .LBB0_46

; #define LAS __attribute__((address_space(3)))
; __device__ __forceinline__ void p0_transpose_item64(const WsRef& wsr, const float* W, int K, int N, bf16* WT, LAS float* scr, int item, int lane, const float* kscale = nullptr) {
;     ...
;     for (int i = 0; i < 16; ++i) v[i] = *(const f32x4*)(W + (size_t)(k0 + 4 * i + kq) * N + n0 + nq * 4);
; #pragma unroll
;     for (int i = 0; i < 16; ++i) { const int kk = 4 * i + kq; const float sc = kscale ? kscale[k0 + kk] : 1.0f; LAS float* d = scr + kk * 65 + nq * 4;
;         d[0] = v[i][0] * sc; d[1] = v[i][1] * sc; d[2] = v[i][2] * sc; d[3] = v[i][3] * sc; }
.LBB0_46:
	s_waitcnt vmcnt(0)
	v_pk_mul_f32 v[8:9], v[8:9], v[16:17] op_sel_hi:[1,0]
	v_add_u32_e32 v12, 0x2490, v116
	ds_write2_b32 v12, v8, v9 offset1:1
	v_pk_mul_f32 v[8:9], v[10:11], v[16:17] op_sel_hi:[1,0]
	v_add_u32_e32 v10, 0x2498, v116
	ds_write2_b32 v10, v8, v9 offset1:1
	s_and_b64 vcc, exec, s[0:1]
	v_add_u32_e32 v9, 0x28a0, v116
	v_add_u32_e32 v10, 0x28a8, v116
	s_cbranch_vccnz .LBB0_55
	s_ashr_i32 s35, s34, 31
	v_lshl_add_u64 v[12:13], s[34:35], 0, v[64:65]
	v_lshl_add_u64 v[12:13], v[12:13], 2, s[14:15]
	global_load_dword v14, v[12:13], off offset:224 nt
	global_load_dword v8, v[12:13], off offset:240 nt
	s_waitcnt vmcnt(1)
	v_pk_mul_f32 v[12:13], v[4:5], v[14:15] op_sel_hi:[1,0]
	v_pk_mul_f32 v[14:15], v[6:7], v[14:15] op_sel_hi:[1,0]
	ds_write2_b32 v9, v12, v13 offset1:1
	ds_write2_b32 v10, v14, v15 offset1:1
	s_cbranch_execnz .LBB0_20
	s_branch .LBB0_56

; __global__ void __launch_bounds__(512, 2) fwd_mega(Args a) {
;     ...
;         for (int m = gw; m < M; m += 2 * NGW) {
;             const int m2 = (m + NGW < M) ? m + NGW : m;
;             const f32x4* xr0 = (const f32x4*)(x + (size_t)m * D) + 2 * lane; const f32x4* xr1 = (const f32x4*)(x + (size_t)m2 * D) + 2 * lane;
;             f32x4 v0[4], v1[4]; float s0 = 0.f, s1 = 0.f;
; #pragma unroll
;             for (int j = 0; j < 2; ++j) { v0[2 * j] = xr0[128 * j]; v0[2 * j + 1] = xr0[128 * j + 1]; v1[2 * j] = xr1[128 * j]; v1[2 * j + 1] = xr1[128 * j + 1]; }
; #pragma unroll
;             for (int j = 0; j < 4; ++j) { s0 += (v0[j].x * v0[j].x + v0[j].y * v0[j].y) + (v0[j].z * v0[j].z + v0[j].w * v0[j].w); s1 += (v1[j].x * v1[j].x + v1[j].y * v1[j].y) + (v1[j].z * v1[j].z + v1[j].w * v1[j].w); }
; #pragma unroll
;             for (int o = 1; o < 64; o <<= 1) { s0 += __shfl_xor(s0, o); s1 += __shfl_xor(s1, o); }
;             if (lane == 0) { RSQX[m] = s0; RSQX[m2] = s1; }
.LBB0_60:
	s_add_i32 s3, s6, s80
	s_cmpk_lt_i32 s3, 0x4000
	s_cselect_b32 s8, s3, s6
	s_ashr_i32 s7, s6, 31
	s_lshl_b64 s[14:15], s[6:7], 12
	s_ashr_i32 s9, s8, 31
	v_lshl_add_u64 v[0:1], v[34:35], 0, s[14:15]
	s_lshl_b64 s[14:15], s[8:9], 12
	global_load_dwordx4 v[28:31], v[0:1], off nt
	global_load_dwordx4 v[24:27], v[0:1], off offset:16 nt
	global_load_dwordx4 v[12:15], v[0:1], off offset:2048 nt
	global_load_dwordx4 v[8:11], v[0:1], off offset:2064 nt
	v_lshl_add_u64 v[0:1], v[34:35], 0, s[14:15]
	global_load_dwordx4 v[20:23], v[0:1], off nt
	global_load_dwordx4 v[16:19], v[0:1], off offset:16 nt
	global_load_dwordx4 v[4:7], v[0:1], off offset:2048 nt
	s_nop 0
	global_load_dwordx4 v[0:3], v[0:1], off offset:2064 nt
	s_waitcnt vmcnt(7)
	v_mul_f32_e32 v43, v29, v29
	v_mul_f32_e32 v44, v31, v31
	s_waitcnt vmcnt(6)
	v_mul_f32_e32 v45, v25, v25
	v_mul_f32_e32 v46, v27, v27
	s_waitcnt vmcnt(5)
	v_mul_f32_e32 v47, v13, v13
	v_mul_f32_e32 v48, v15, v15
	v_fmac_f32_e32 v43, v28, v28
	v_fmac_f32_e32 v44, v30, v30
	s_waitcnt vmcnt(3)
	v_mul_f32_e32 v51, v21, v21
	v_mul_f32_e32 v52, v23, v23
	v_fmac_f32_e32 v45, v24, v24
	v_fmac_f32_e32 v46, v26, v26
	s_waitcnt vmcnt(2)
	v_mul_f32_e32 v53, v17, v17
	v_mul_f32_e32 v54, v19, v19
	v_fmac_f32_e32 v47, v12, v12
	v_fmac_f32_e32 v48, v14, v14
	s_waitcnt vmcnt(1)
	v_mul_f32_e32 v55, v5, v5
	v_mul_f32_e32 v56, v7, v7
	v_add_f32_e32 v43, v43, v44
	v_fmac_f32_e32 v51, v20, v20
	v_fmac_f32_e32 v52, v22, v22
	v_add_f32_e32 v44, v45, v46
	v_fmac_f32_e32 v53, v16, v16
	v_fmac_f32_e32 v54, v18, v18
	v_mul_f32_e32 v49, v9, v9
	v_mul_f32_e32 v50, v11, v11
	s_waitcnt vmcnt(0)
	v_mul_f32_e32 v57, v1, v1
	v_mul_f32_e32 v58, v3, v3
	v_add_f32_e32 v45, v47, v48
	v_fmac_f32_e32 v55, v4, v4
	v_fmac_f32_e32 v56, v6, v6
	v_add_f32_e32 v47, v51, v52
	v_add_f32_e32 v43, v43, v44
	v_add_f32_e32 v44, v53, v54
	v_fmac_f32_e32 v49, v8, v8
	v_fmac_f32_e32 v50, v10, v10
	v_fmac_f32_e32 v57, v0, v0
	v_fmac_f32_e32 v58, v2, v2
	v_add_f32_e32 v48, v55, v56
	v_add_f32_e32 v44, v47, v44
	v_add_f32_e32 v46, v49, v50
	v_add_f32_e32 v49, v57, v58
	v_add_f32_e32 v43, v43, v45
	v_add_f32_e32 v44, v44, v48
	v_add_f32_e32 v43, v43, v46
	v_add_f32_e32 v44, v44, v49
	ds_bpermute_b32 v45, v32, v43
	ds_bpermute_b32 v46, v32, v44
	s_waitcnt lgkmcnt(1)
	v_add_f32_e32 v43, v43, v45
	s_waitcnt lgkmcnt(0)
	v_add_f32_e32 v44, v44, v46
	ds_bpermute_b32 v45, v38, v43
	ds_bpermute_b32 v46, v38, v44
	s_waitcnt lgkmcnt(1)
	v_add_f32_e32 v43, v43, v45
	s_waitcnt lgkmcnt(0)
	v_add_f32_e32 v44, v44, v46
	ds_bpermute_b32 v45, v39, v43
	ds_bpermute_b32 v46, v39, v44
	s_waitcnt lgkmcnt(1)
	v_add_f32_e32 v43, v43, v45
	s_waitcnt lgkmcnt(0)
	v_add_f32_e32 v44, v44, v46
	ds_bpermute_b32 v45, v40, v43
	ds_bpermute_b32 v46, v40, v44
	s_waitcnt lgkmcnt(1)
	v_add_f32_e32 v43, v43, v45
	s_waitcnt lgkmcnt(0)
	v_add_f32_e32 v44, v44, v46
	ds_bpermute_b32 v45, v41, v43
	ds_bpermute_b32 v46, v41, v44
	s_waitcnt lgkmcnt(1)
	v_add_f32_e32 v43, v43, v45
	s_waitcnt lgkmcnt(0)
	v_add_f32_e32 v44, v44, v46
	ds_bpermute_b32 v45, v42, v43
	ds_bpermute_b32 v46, v42, v44
	s_and_saveexec_b64 s[14:15], s[0:1]
	s_cbranch_execz .LBB0_62
	s_lshl_b64 s[16:17], s[8:9], 2
	s_add_u32 s16, s28, s16
	s_addc_u32 s17, s29, s17
	s_lshl_b64 s[26:27], s[6:7], 2
	s_add_u32 s26, s28, s26
	s_waitcnt lgkmcnt(1)
	v_add_f32_e32 v43, v43, v45
	s_addc_u32 s27, s29, s27
	s_waitcnt lgkmcnt(0)
	v_add_f32_e32 v44, v44, v46
	global_store_dword v33, v43, s[26:27]
	global_store_dword v33, v44, s[16:17]

; __device__ __forceinline__ unsigned pk2(float lo, float hi) { return pg8::cvt_pk_bf16(lo, hi); }
; __device__ __forceinline__ void rms_row_to_bf16(const float* xrow, const float* w, bf16* orow, int lane) {
;     const f32x4* xr = (const f32x4*)xrow + lane; const f32x4* wr = (const f32x4*)w + lane;
;     f32x4 v[4]; float s = 0.f;
; #pragma unroll
;     for (int j = 0; j < 4; ++j) { v[j] = xr[64 * j]; s += (v[j].x * v[j].x + v[j].y * v[j].y) + (v[j].z * v[j].z + v[j].w * v[j].w); }
;     const float rstd = rsqrtf(wave_sum(s) * (1.f / D) + EPS);
;     u32x2* o8 = (u32x2*)orow + lane;
; #pragma unroll
;     for (int j = 0; j < 4; ++j) { const f32x4 ww = wr[64 * j]; u32x2 o; o.x = pk2(v[j].x * rstd * ww.x, v[j].y * rstd * ww.y); o.y = pk2(v[j].z * rstd * ww.z, v[j].w * rstd * ww.w); o8[64 * j] = o; }
; }
; __global__ void __launch_bounds__(512, 2) fwd_mega(Args a) {
;     ...
;         for (int m = gw; m < BATCH * 256; m += NGW) rms_row_to_bf16(mem + (size_t)m * D, a.in[15], MEMN + (size_t)m * D, lane);
.LBB0_68:
	global_load_dwordx4 v[14:17], v[4:5], off offset:-2048 nt
	global_load_dwordx4 v[18:21], v[4:5], off offset:-1024 nt
	global_load_dwordx4 v[22:25], v[4:5], off nt
	global_load_dwordx4 v[26:29], v[4:5], off offset:1024 nt
	global_load_dwordx4 v[30:33], v[0:1], off nt
	s_add_i32 s8, s8, s80
	v_lshl_add_u64 v[4:5], v[4:5], 0, s[6:7]
	s_cmpk_gt_i32 s8, 0x1ff
	s_waitcnt vmcnt(4)
	v_pk_mul_f32 v[34:35], v[16:17], v[16:17]
	v_pk_mul_f32 v[36:37], v[14:15], v[14:15]
	s_waitcnt vmcnt(3)
	v_pk_mul_f32 v[38:39], v[20:21], v[20:21]
	v_pk_mul_f32 v[40:41], v[18:19], v[18:19]
	v_pk_mov_b32 v[46:47], v[36:37], v[34:35] op_sel:[1,0]
	v_mov_b32_e32 v37, v35
	v_pk_mov_b32 v[34:35], v[40:41], v[38:39] op_sel:[1,0]
	v_mov_b32_e32 v41, v39
	s_waitcnt vmcnt(1)
	v_mul_f32_e32 v45, v27, v27
	v_mul_f32_e32 v42, v23, v23
	v_mul_f32_e32 v44, v25, v25
	v_pk_add_f32 v[36:37], v[46:47], v[36:37]
	v_pk_add_f32 v[34:35], v[34:35], v[40:41]
	v_mul_f32_e32 v13, v26, v26
	v_mul_f32_e32 v48, v28, v28
	v_mul_f32_e32 v49, v29, v29
	v_pk_fma_f32 v[38:39], v[22:23], v[22:23], v[42:43] op_sel_hi:[1,1,0]
	v_pk_fma_f32 v[42:43], v[24:25], v[24:25], v[44:45] op_sel_hi:[1,1,0]
	v_pk_add_f32 v[36:37], v[36:37], v[36:37] op_sel:[0,1] op_sel_hi:[1,0]
	v_pk_add_f32 v[34:35], v[34:35], v[34:35] op_sel:[0,1] op_sel_hi:[1,0]
	v_mov_b32_e32 v39, v48
	v_mov_b32_e32 v43, v49
	v_mov_b32_e32 v37, v13
	v_mov_b32_e32 v35, v45
	v_pk_add_f32 v[38:39], v[38:39], v[42:43]
	v_pk_add_f32 v[34:35], v[36:37], v[34:35]
	s_nop 0
	v_pk_add_f32 v[34:35], v[34:35], v[38:39]
	s_nop 0
	v_add_f32_e32 v13, v34, v35
	ds_bpermute_b32 v34, v6, v13
	s_waitcnt lgkmcnt(0)
	v_add_f32_e32 v13, v13, v34
	ds_bpermute_b32 v34, v7, v13
	s_waitcnt lgkmcnt(0)
	v_add_f32_e32 v13, v13, v34
	ds_bpermute_b32 v34, v8, v13
	s_waitcnt lgkmcnt(0)
	v_add_f32_e32 v13, v13, v34
	ds_bpermute_b32 v34, v9, v13
	s_waitcnt lgkmcnt(0)
	v_add_f32_e32 v13, v13, v34
	ds_bpermute_b32 v34, v10, v13
	s_waitcnt lgkmcnt(0)
	v_add_f32_e32 v13, v13, v34
	ds_bpermute_b32 v34, v11, v13
	s_waitcnt lgkmcnt(0)
	v_add_f32_e32 v13, v13, v34
	v_fmamk_f32 v13, v13, 0x3a800000, v12
	v_mul_f32_e32 v34, 0x4b800000, v13
	v_cmp_gt_f32_e32 vcc, s3, v13
	s_nop 1
	v_cndmask_b32_e32 v13, v13, v34, vcc
	v_rsq_f32_e32 v13, v13
	s_nop 0
	v_mul_f32_e32 v34, 0x45800000, v13
	v_cndmask_b32_e32 v34, v13, v34, vcc
	v_pk_mul_f32 v[14:15], v[14:15], v[34:35] op_sel_hi:[1,0]
	v_pk_mul_f32 v[16:17], v[16:17], v[34:35] op_sel_hi:[1,0]
	s_waitcnt vmcnt(0)
	v_pk_mul_f32 v[14:15], v[30:31], v[14:15]
	v_pk_mul_f32 v[16:17], v[32:33], v[16:17]
	v_cvt_pk_bf16_f32 v14, v14, v15
	v_cvt_pk_bf16_f32 v15, v16, v17
	global_store_dwordx2 v[2:3], v[14:15], off offset:-1536
	global_load_dwordx4 v[14:17], v[0:1], off offset:1024 nt
	v_pk_mul_f32 v[18:19], v[18:19], v[34:35] op_sel_hi:[1,0]
	v_pk_mul_f32 v[20:21], v[20:21], v[34:35] op_sel_hi:[1,0]
	s_waitcnt vmcnt(0)
	v_pk_mul_f32 v[14:15], v[14:15], v[18:19]
	v_pk_mul_f32 v[16:17], v[16:17], v[20:21]
	v_cvt_pk_bf16_f32 v14, v14, v15
	v_cvt_pk_bf16_f32 v15, v16, v17
	global_store_dwordx2 v[2:3], v[14:15], off offset:-1024
	global_load_dwordx4 v[14:17], v[0:1], off offset:2048 nt
	v_pk_mul_f32 v[18:19], v[22:23], v[34:35] op_sel_hi:[1,0]
	v_pk_mul_f32 v[20:21], v[24:25], v[34:35] op_sel_hi:[1,0]
	s_waitcnt vmcnt(0)
	v_pk_mul_f32 v[14:15], v[14:15], v[18:19]
	v_pk_mul_f32 v[16:17], v[16:17], v[20:21]
	v_cvt_pk_bf16_f32 v14, v14, v15
	v_cvt_pk_bf16_f32 v15, v16, v17
	global_store_dwordx2 v[2:3], v[14:15], off offset:-512
	global_load_dwordx4 v[14:17], v[0:1], off offset:3072 nt
	v_pk_mul_f32 v[18:19], v[26:27], v[34:35] op_sel_hi:[1,0]
	v_pk_mul_f32 v[20:21], v[28:29], v[34:35] op_sel_hi:[1,0]
	s_waitcnt vmcnt(0)
	v_pk_mul_f32 v[14:15], v[14:15], v[18:19]
	v_pk_mul_f32 v[16:17], v[16:17], v[20:21]
	v_cvt_pk_bf16_f32 v14, v14, v15
	v_cvt_pk_bf16_f32 v15, v16, v17
	global_store_dwordx2 v[2:3], v[14:15], off
	v_lshl_add_u64 v[2:3], v[2:3], 0, s[0:1]
	s_cbranch_scc0 .LBB0_68

; #define LAS __attribute__((address_space(3)))
; __device__ __forceinline__ void kvproj_coop(LAS unsigned char* lds, int t, const bf16* MEMN, const bf16* WXKV, bf16* Kx, bf16* VTx, int tid) {
;     const int lane = tid & 63, wave = tid >> 6, fr = lane & 15, fq = lane >> 4;
;     const int mt = (t >> 5) * 64, nt = (t & 31) * 64, mrow = (wave & 3) * 16, ncol = (wave >> 2) * 32;
;     LAS bf16* As = (LAS bf16*)lds; LAS bf16* Bs = (LAS bf16*)(lds + 64 * 520 * 2);
;     f32x4 c0 = (f32x4){0.f, 0.f, 0.f, 0.f}, c1 = c0;
;     for (int kc = 0; kc < 2; ++kc) {
;         u32x4 ra[8], rb[8];
; #pragma unroll
;         for (int i = 0; i < 8; ++i) { const int id = tid + 512 * i, r = id >> 6, ch = id & 63;
;             ra[i] = *(const u32x4*)(MEMN + (size_t)(mt + r) * D + kc * 512 + ch * 8); rb[i] = *(const u32x4*)(WXKV + (size_t)(nt + r) * D + kc * 512 + ch * 8); }
;         if (kc) __syncthreads();
; #pragma unroll
;         for (int i = 0; i < 8; ++i) { const int id = tid + 512 * i, r = id >> 6, ch = id & 63; *(LAS u32x4*)(As + r * 520 + ch * 8) = ra[i]; *(LAS u32x4*)(Bs + r * 520 + ch * 8) = rb[i]; }
;         __syncthreads();
; #pragma unroll
;         for (int kk = 0; kk < 16; ++kk) { const bf16x8 av = *(const LAS bf16x8*)(As + (mrow + fr) * 520 + kk * 32 + fq * 8);
.LBB0_283:
	s_and_b32 s1, s3, 0xffffffc0
	v_or_b32_e32 v10, s1, v26
	v_ashrrev_i32_e32 v11, 31, v10
	v_lshlrev_b64 v[10:11], 11, v[10:11]
	v_lshl_add_u64 v[106:107], v[8:9], 0, v[10:11]
	v_or_b32_e32 v10, s1, v27
	s_and_b32 s0, s29, 0x7c0
	v_ashrrev_i32_e32 v11, 31, v10
	v_add_lshl_u32 v4, s0, v24, 11
	v_lshlrev_b64 v[10:11], 11, v[10:11]
	v_lshl_add_u64 v[0:1], v[6:7], 0, v[4:5]
	v_or_b32_e32 v4, s0, v26
	v_lshl_add_u64 v[104:105], v[8:9], 0, v[10:11]
	v_or_b32_e32 v10, s1, v28
	v_lshlrev_b32_e32 v4, 11, v4
	v_ashrrev_i32_e32 v11, 31, v10
	v_lshl_add_u64 v[110:111], v[6:7], 0, v[4:5]
	v_or_b32_e32 v4, s0, v27
	v_lshlrev_b64 v[10:11], 11, v[10:11]
	v_lshlrev_b32_e32 v4, 11, v4
	v_lshl_add_u64 v[112:113], v[8:9], 0, v[10:11]
	v_or_b32_e32 v10, s1, v29
	v_lshl_add_u64 v[102:103], v[6:7], 0, v[4:5]
	v_or_b32_e32 v4, s0, v28
	v_ashrrev_i32_e32 v11, 31, v10
	v_lshlrev_b32_e32 v4, 11, v4
	v_lshlrev_b64 v[10:11], 11, v[10:11]
	v_lshl_add_u64 v[108:109], v[6:7], 0, v[4:5]
	v_or_b32_e32 v4, s0, v29
	v_lshl_add_u64 v[116:117], v[8:9], 0, v[10:11]
	v_or_b32_e32 v10, s1, v30
	v_lshlrev_b32_e32 v4, 11, v4
	v_ashrrev_i32_e32 v11, 31, v10
	v_lshl_add_u64 v[114:115], v[6:7], 0, v[4:5]
	v_or_b32_e32 v4, s0, v30
	v_lshlrev_b64 v[10:11], 11, v[10:11]
	v_lshlrev_b32_e32 v4, 11, v4
	v_lshl_add_u64 v[120:121], v[8:9], 0, v[10:11]
	v_or_b32_e32 v10, s1, v31
	v_lshl_add_u64 v[118:119], v[6:7], 0, v[4:5]
	v_or_b32_e32 v4, s0, v31
	v_ashrrev_i32_e32 v11, 31, v10
	v_add_u32_e32 v2, s1, v24
	v_lshlrev_b32_e32 v4, 11, v4
	v_lshlrev_b64 v[10:11], 11, v[10:11]
	v_ashrrev_i32_e32 v3, 31, v2
	v_lshl_add_u64 v[122:123], v[6:7], 0, v[4:5]
	v_lshl_add_u64 v[124:125], v[8:9], 0, v[10:11]
	v_or_b32_e32 v4, s0, v25
	v_or_b32_e32 v10, s1, v25
	v_lshlrev_b64 v[2:3], 11, v[2:3]
	v_lshlrev_b32_e32 v4, 11, v4
	v_ashrrev_i32_e32 v11, 31, v10
	v_lshl_add_u64 v[126:127], v[6:7], 0, v[4:5]
	v_lshlrev_b64 v[10:11], 11, v[10:11]
	v_lshl_add_u64 v[2:3], v[8:9], 0, v[2:3]
	v_lshl_add_u64 v[130:131], v[8:9], 0, v[10:11]
	global_load_dwordx4 v[10:13], v[126:127], off nt
	global_load_dwordx4 v[14:17], v[130:131], off nt
	global_load_dwordx4 v[46:49], v[122:123], off nt
	global_load_dwordx4 v[50:53], v[124:125], off nt
	global_load_dwordx4 v[54:57], v[118:119], off nt
	global_load_dwordx4 v[58:61], v[120:121], off nt
	global_load_dwordx4 v[62:65], v[114:115], off nt
	global_load_dwordx4 v[66:69], v[116:117], off nt
	global_load_dwordx4 v[70:73], v[108:109], off nt
	global_load_dwordx4 v[74:77], v[112:113], off nt
	global_load_dwordx4 v[78:81], v[102:103], off nt
	global_load_dwordx4 v[82:85], v[104:105], off nt
	global_load_dwordx4 v[86:89], v[110:111], off nt
	global_load_dwordx4 v[90:93], v[106:107], off nt
	global_load_dwordx4 v[94:97], v[2:3], off nt
	global_load_dwordx4 v[98:101], v[0:1], off nt
	s_and_b32 s1, s3, 0xc0
	s_waitcnt vmcnt(0)
	ds_write_b128 v32, v[14:17]
	ds_write_b128 v33, v[10:13]
	ds_write_b128 v34, v[50:53]
	ds_write_b128 v35, v[46:49]
	ds_write_b128 v32, v[58:61] offset:16640
	ds_write_b128 v36, v[54:57]
	ds_write_b128 v37, v[66:69]
	ds_write_b128 v38, v[62:65]
	ds_write_b128 v32, v[74:77] offset:33280
	ds_write_b128 v39, v[70:73]
	ds_write_b128 v40, v[82:85]
	ds_write_b128 v41, v[78:81]
	ds_write_b128 v32, v[90:93] offset:49920
	ds_write_b128 v42, v[86:89]
	ds_write_b128 v43, v[94:97]
	ds_write_b128 v44, v[98:101]
	s_waitcnt lgkmcnt(0)
	s_barrier
	ds_read_b128 v[10:13], v23
	ds_read_b128 v[14:17], v22
	ds_read_b128 v[46:49], v22 offset:64
	ds_read_b128 v[50:53], v23 offset:64
	s_waitcnt lgkmcnt(2)
	v_mfma_f32_16x16x32_bf16 v[10:13], v[10:13], v[14:17], 0
	ds_read_b128 v[54:57], v23 offset:16640
	ds_read_b128 v[58:61], v23 offset:16704
	s_waitcnt lgkmcnt(2)
	v_mfma_f32_16x16x32_bf16 v[10:13], v[50:53], v[46:49], v[10:13]
	ds_read_b128 v[50:53], v23 offset:128
	s_waitcnt lgkmcnt(2)
	v_mfma_f32_16x16x32_bf16 v[14:17], v[54:57], v[14:17], 0
	s_waitcnt lgkmcnt(1)
	v_mfma_f32_16x16x32_bf16 v[14:17], v[58:61], v[46:49], v[14:17]
	ds_read_b128 v[46:49], v22 offset:128
	ds_read_b128 v[54:57], v22 offset:192
	ds_read_b128 v[58:61], v23 offset:192
	s_waitcnt lgkmcnt(2)
	v_mfma_f32_16x16x32_bf16 v[10:13], v[50:53], v[46:49], v[10:13]
	ds_read_b128 v[50:53], v23 offset:16768
	ds_read_b128 v[62:65], v23 offset:16832
	s_waitcnt lgkmcnt(1)
	v_mfma_f32_16x16x32_bf16 v[14:17], v[50:53], v[46:49], v[14:17]
	ds_read_b128 v[46:49], v23 offset:256
	v_mfma_f32_16x16x32_bf16 v[10:13], v[58:61], v[54:57], v[10:13]
	s_waitcnt lgkmcnt(1)
	v_mfma_f32_16x16x32_bf16 v[14:17], v[62:65], v[54:57], v[14:17]
	ds_read_b128 v[50:53], v22 offset:256
	ds_read_b128 v[54:57], v22 offset:320
	ds_read_b128 v[58:61], v23 offset:320
	s_waitcnt lgkmcnt(2)
	v_mfma_f32_16x16x32_bf16 v[10:13], v[46:49], v[50:53], v[10:13]
	ds_read_b128 v[46:49], v23 offset:16896
	ds_read_b128 v[62:65], v23 offset:16960
	s_waitcnt lgkmcnt(1)
	v_mfma_f32_16x16x32_bf16 v[14:17], v[46:49], v[50:53], v[14:17]
	ds_read_b128 v[46:49], v23 offset:384
	v_mfma_f32_16x16x32_bf16 v[10:13], v[58:61], v[54:57], v[10:13]
	s_waitcnt lgkmcnt(1)
	v_mfma_f32_16x16x32_bf16 v[14:17], v[62:65], v[54:57], v[14:17]
	ds_read_b128 v[50:53], v22 offset:384
	ds_read_b128 v[54:57], v22 offset:448
	ds_read_b128 v[58:61], v23 offset:448
	s_waitcnt lgkmcnt(2)
	v_mfma_f32_16x16x32_bf16 v[10:13], v[46:49], v[50:53], v[10:13]
	ds_read_b128 v[46:49], v23 offset:17024
	ds_read_b128 v[62:65], v23 offset:17088
	s_waitcnt lgkmcnt(1)
	v_mfma_f32_16x16x32_bf16 v[14:17], v[46:49], v[50:53], v[14:17]
	ds_read_b128 v[46:49], v23 offset:512
	v_mfma_f32_16x16x32_bf16 v[10:13], v[58:61], v[54:57], v[10:13]
	s_waitcnt lgkmcnt(1)
; #define LAS __attribute__((address_space(3)))
; #define MFMA16(a, b, c) __builtin_amdgcn_mfma_f32_16x16x32_bf16((a), (b), (c), 0, 0, 0)
; __device__ __forceinline__ void kvproj_coop(LAS unsigned char* lds, int t, const bf16* MEMN, const bf16* WXKV, bf16* Kx, bf16* VTx, int tid) {
;     ...
;     for (int kc = 0; kc < 2; ++kc) {
;         u32x4 ra[8], rb[8];
; #pragma unroll
;         for (int i = 0; i < 8; ++i) { const int id = tid + 512 * i, r = id >> 6, ch = id & 63;
;             ra[i] = *(const u32x4*)(MEMN + (size_t)(mt + r) * D + kc * 512 + ch * 8); rb[i] = *(const u32x4*)(WXKV + (size_t)(nt + r) * D + kc * 512 + ch * 8); }
;         if (kc) __syncthreads();
; #pragma unroll
;         for (int i = 0; i < 8; ++i) { const int id = tid + 512 * i, r = id >> 6, ch = id & 63; *(LAS u32x4*)(As + r * 520 + ch * 8) = ra[i]; *(LAS u32x4*)(Bs + r * 520 + ch * 8) = rb[i]; }
;         __syncthreads();
; #pragma unroll
;         for (int kk = 0; kk < 16; ++kk) { const bf16x8 av = *(const LAS bf16x8*)(As + (mrow + fr) * 520 + kk * 32 + fq * 8);
;             const bf16x8 b0 = *(const LAS bf16x8*)(Bs + (ncol + fr) * 520 + kk * 32 + fq * 8), b1 = *(const LAS bf16x8*)(Bs + (ncol + 16 + fr) * 520 + kk * 32 + fq * 8);
;             c0 = MFMA16(b0, av, c0); c1 = MFMA16(b1, av, c1); }
	v_mfma_f32_16x16x32_bf16 v[14:17], v[62:65], v[54:57], v[14:17]
	ds_read_b128 v[50:53], v22 offset:512
	ds_read_b128 v[54:57], v22 offset:576
	ds_read_b128 v[58:61], v23 offset:576
	s_waitcnt lgkmcnt(2)
	v_mfma_f32_16x16x32_bf16 v[10:13], v[46:49], v[50:53], v[10:13]
	ds_read_b128 v[46:49], v23 offset:17152
	ds_read_b128 v[62:65], v23 offset:17216
	s_waitcnt lgkmcnt(1)
	v_mfma_f32_16x16x32_bf16 v[14:17], v[46:49], v[50:53], v[14:17]
	ds_read_b128 v[46:49], v23 offset:640
	v_mfma_f32_16x16x32_bf16 v[10:13], v[58:61], v[54:57], v[10:13]
	s_waitcnt lgkmcnt(1)
	v_mfma_f32_16x16x32_bf16 v[14:17], v[62:65], v[54:57], v[14:17]
	ds_read_b128 v[50:53], v22 offset:640
	ds_read_b128 v[54:57], v22 offset:704
	ds_read_b128 v[58:61], v23 offset:704
	s_waitcnt lgkmcnt(2)
	v_mfma_f32_16x16x32_bf16 v[10:13], v[46:49], v[50:53], v[10:13]
	ds_read_b128 v[46:49], v23 offset:17280
	ds_read_b128 v[62:65], v23 offset:17344
	s_waitcnt lgkmcnt(1)
	v_mfma_f32_16x16x32_bf16 v[14:17], v[46:49], v[50:53], v[14:17]
	ds_read_b128 v[46:49], v23 offset:768
	v_mfma_f32_16x16x32_bf16 v[10:13], v[58:61], v[54:57], v[10:13]
	s_waitcnt lgkmcnt(1)
	v_mfma_f32_16x16x32_bf16 v[14:17], v[62:65], v[54:57], v[14:17]
	ds_read_b128 v[50:53], v22 offset:768
	ds_read_b128 v[54:57], v22 offset:832
	ds_read_b128 v[58:61], v23 offset:832
	s_waitcnt lgkmcnt(2)
	v_mfma_f32_16x16x32_bf16 v[10:13], v[46:49], v[50:53], v[10:13]
	ds_read_b128 v[46:49], v23 offset:17408
	ds_read_b128 v[62:65], v23 offset:17472
	s_waitcnt lgkmcnt(1)
	v_mfma_f32_16x16x32_bf16 v[14:17], v[46:49], v[50:53], v[14:17]
	ds_read_b128 v[46:49], v23 offset:896
	v_mfma_f32_16x16x32_bf16 v[10:13], v[58:61], v[54:57], v[10:13]
	s_waitcnt lgkmcnt(1)
	v_mfma_f32_16x16x32_bf16 v[14:17], v[62:65], v[54:57], v[14:17]
	ds_read_b128 v[50:53], v22 offset:896
	ds_read_b128 v[54:57], v22 offset:960
	ds_read_b128 v[58:61], v23 offset:960
	s_waitcnt lgkmcnt(2)
	v_mfma_f32_16x16x32_bf16 v[10:13], v[46:49], v[50:53], v[10:13]
	ds_read_b128 v[46:49], v23 offset:17536
	ds_read_b128 v[62:65], v23 offset:17600
	s_waitcnt lgkmcnt(1)
	v_mfma_f32_16x16x32_bf16 v[14:17], v[46:49], v[50:53], v[14:17]
	global_load_dwordx4 v[46:49], v[130:131], off offset:1024 nt
	global_load_dwordx4 v[50:53], v[126:127], off offset:1024 nt
	global_load_dwordx4 v[66:69], v[124:125], off offset:1024 nt
	global_load_dwordx4 v[70:73], v[122:123], off offset:1024 nt
	global_load_dwordx4 v[74:77], v[120:121], off offset:1024 nt
	global_load_dwordx4 v[78:81], v[118:119], off offset:1024 nt
	global_load_dwordx4 v[82:85], v[116:117], off offset:1024 nt
	global_load_dwordx4 v[86:89], v[114:115], off offset:1024 nt
	global_load_dwordx4 v[90:93], v[112:113], off offset:1024 nt
	global_load_dwordx4 v[94:97], v[108:109], off offset:1024 nt
	global_load_dwordx4 v[98:101], v[104:105], off offset:1024 nt
	s_nop 0
	global_load_dwordx4 v[102:105], v[102:103], off offset:1024 nt
	s_nop 0
	global_load_dwordx4 v[106:109], v[106:107], off offset:1024 nt
	s_nop 0
	global_load_dwordx4 v[110:113], v[110:111], off offset:1024 nt
	s_nop 0
	global_load_dwordx4 v[114:117], v[2:3], off offset:1024 nt
	s_nop 0
	global_load_dwordx4 v[0:3], v[0:1], off offset:1024 nt
	s_waitcnt lgkmcnt(0)
	s_barrier
	v_mfma_f32_16x16x32_bf16 v[10:13], v[58:61], v[54:57], v[10:13]
	s_waitcnt vmcnt(15)
	ds_write_b128 v32, v[46:49]
	s_waitcnt vmcnt(14)
	ds_write_b128 v33, v[50:53]
	s_waitcnt vmcnt(13)
	ds_write_b128 v34, v[66:69]
	s_waitcnt vmcnt(12)
	ds_write_b128 v35, v[70:73]
	s_waitcnt vmcnt(11)
	ds_write_b128 v32, v[74:77] offset:16640
	s_waitcnt vmcnt(10)
	ds_write_b128 v36, v[78:81]
	s_waitcnt vmcnt(9)
	ds_write_b128 v37, v[82:85]
	s_waitcnt vmcnt(8)
	ds_write_b128 v38, v[86:89]
	s_waitcnt vmcnt(7)
	ds_write_b128 v32, v[90:93] offset:33280
	s_waitcnt vmcnt(6)
	ds_write_b128 v39, v[94:97]
	s_waitcnt vmcnt(5)
	ds_write_b128 v40, v[98:101]
	s_waitcnt vmcnt(4)
	ds_write_b128 v41, v[102:105]
	s_waitcnt vmcnt(3)
	ds_write_b128 v32, v[106:109] offset:49920
	s_waitcnt vmcnt(2)
	ds_write_b128 v42, v[110:113]
	s_waitcnt vmcnt(1)
	ds_write_b128 v43, v[114:117]
	s_waitcnt vmcnt(0)
	ds_write_b128 v44, v[0:3]
	s_waitcnt lgkmcnt(0)
	s_barrier
; #define LAS __attribute__((address_space(3)))
; __device__ __forceinline__ unsigned pk2(float lo, float hi) { return pg8::cvt_pk_bf16(lo, hi); }
; #define MFMA16(a, b, c) __builtin_amdgcn_mfma_f32_16x16x32_bf16((a), (b), (c), 0, 0, 0)
; __device__ __forceinline__ void kvproj_coop(LAS unsigned char* lds, int t, const bf16* MEMN, const bf16* WXKV, bf16* Kx, bf16* VTx, int tid) {
;     ...
; #pragma unroll
;         for (int kk = 0; kk < 16; ++kk) { const bf16x8 av = *(const LAS bf16x8*)(As + (mrow + fr) * 520 + kk * 32 + fq * 8);
;             const bf16x8 b0 = *(const LAS bf16x8*)(Bs + (ncol + fr) * 520 + kk * 32 + fq * 8), b1 = *(const LAS bf16x8*)(Bs + (ncol + 16 + fr) * 520 + kk * 32 + fq * 8);
;             c0 = MFMA16(b0, av, c0); c1 = MFMA16(b1, av, c1); }
;     }
;     __syncthreads();
;     const int row = mt + mrow + fr, b = row >> 8, key = row & 255;
; #pragma unroll
;     for (int j = 0; j < 2; ++j) { const f32x4 v = j ? c1 : c0; const int n = nt + ncol + 16 * j + 4 * fq; const bool isv = n >= 1024; const int nn = isv ? n - 1024 : n, h = nn >> 8, d = nn & 255;
;         const unsigned w0 = pk2(v[0], v[1]), w1 = pk2(v[2], v[3]);
;         if (!isv) { u32x2 w; w.x = w0; w.y = w1; *(u32x2*)(Kx + (size_t)(b * 4 + h) * 65536 + key * 256 + d) = w; }
;         else { bf16* base = VTx + (size_t)(b * 4 + h) * 65536 + key;
;             base[(d + 0) * 256] = (bf16)(w0 & 0xffffu); base[(d + 1) * 256] = (bf16)(w0 >> 16); base[(d + 2) * 256] = (bf16)(w1 & 0xffffu); base[(d + 3) * 256] = (bf16)(w1 >> 16); } }
	ds_read_b128 v[0:3], v23
	v_mfma_f32_16x16x32_bf16 v[14:17], v[62:65], v[54:57], v[14:17]
	ds_read_b128 v[46:49], v22
	ds_read_b128 v[50:53], v22 offset:64
	ds_read_b128 v[54:57], v23 offset:64
	s_waitcnt lgkmcnt(2)
	v_mfma_f32_16x16x32_bf16 v[0:3], v[0:3], v[46:49], v[10:13]
	s_nop 2
	ds_read_b128 v[10:13], v23 offset:16640
	ds_read_b128 v[58:61], v23 offset:16704
	s_waitcnt lgkmcnt(1)
	v_mfma_f32_16x16x32_bf16 v[10:13], v[10:13], v[46:49], v[14:17]
	s_nop 2
	ds_read_b128 v[14:17], v23 offset:128
	v_mfma_f32_16x16x32_bf16 v[0:3], v[54:57], v[50:53], v[0:3]
	s_waitcnt lgkmcnt(1)
	v_mfma_f32_16x16x32_bf16 v[10:13], v[58:61], v[50:53], v[10:13]
	ds_read_b128 v[46:49], v22 offset:128
	ds_read_b128 v[50:53], v22 offset:192
	ds_read_b128 v[54:57], v23 offset:192
	s_waitcnt lgkmcnt(2)
	v_mfma_f32_16x16x32_bf16 v[0:3], v[14:17], v[46:49], v[0:3]
	ds_read_b128 v[14:17], v23 offset:16768
	ds_read_b128 v[58:61], v23 offset:16832
	s_waitcnt lgkmcnt(1)
	v_mfma_f32_16x16x32_bf16 v[10:13], v[14:17], v[46:49], v[10:13]
	ds_read_b128 v[14:17], v23 offset:256
	v_mfma_f32_16x16x32_bf16 v[0:3], v[54:57], v[50:53], v[0:3]
	s_waitcnt lgkmcnt(1)
	v_mfma_f32_16x16x32_bf16 v[10:13], v[58:61], v[50:53], v[10:13]
	ds_read_b128 v[46:49], v22 offset:256
	ds_read_b128 v[50:53], v22 offset:320
	ds_read_b128 v[54:57], v23 offset:320
	s_waitcnt lgkmcnt(2)
	v_mfma_f32_16x16x32_bf16 v[0:3], v[14:17], v[46:49], v[0:3]
	ds_read_b128 v[14:17], v23 offset:16896
	ds_read_b128 v[58:61], v23 offset:16960
	s_waitcnt lgkmcnt(1)
	v_mfma_f32_16x16x32_bf16 v[10:13], v[14:17], v[46:49], v[10:13]
	ds_read_b128 v[14:17], v23 offset:384
	v_mfma_f32_16x16x32_bf16 v[0:3], v[54:57], v[50:53], v[0:3]
	s_waitcnt lgkmcnt(1)
	v_mfma_f32_16x16x32_bf16 v[10:13], v[58:61], v[50:53], v[10:13]
	ds_read_b128 v[46:49], v22 offset:384
	ds_read_b128 v[50:53], v22 offset:448
	ds_read_b128 v[54:57], v23 offset:448
	s_waitcnt lgkmcnt(2)
	v_mfma_f32_16x16x32_bf16 v[0:3], v[14:17], v[46:49], v[0:3]
	ds_read_b128 v[14:17], v23 offset:17024
	ds_read_b128 v[58:61], v23 offset:17088
	s_waitcnt lgkmcnt(1)
	v_mfma_f32_16x16x32_bf16 v[10:13], v[14:17], v[46:49], v[10:13]
	ds_read_b128 v[14:17], v23 offset:512
	v_mfma_f32_16x16x32_bf16 v[0:3], v[54:57], v[50:53], v[0:3]
	s_waitcnt lgkmcnt(1)
	v_mfma_f32_16x16x32_bf16 v[10:13], v[58:61], v[50:53], v[10:13]
	ds_read_b128 v[46:49], v22 offset:512
	ds_read_b128 v[50:53], v22 offset:576
	ds_read_b128 v[54:57], v23 offset:576
	s_waitcnt lgkmcnt(2)
	v_mfma_f32_16x16x32_bf16 v[0:3], v[14:17], v[46:49], v[0:3]
	ds_read_b128 v[14:17], v23 offset:17152
	ds_read_b128 v[58:61], v23 offset:17216
	s_waitcnt lgkmcnt(1)
	v_mfma_f32_16x16x32_bf16 v[10:13], v[14:17], v[46:49], v[10:13]
	ds_read_b128 v[14:17], v23 offset:640
	v_mfma_f32_16x16x32_bf16 v[0:3], v[54:57], v[50:53], v[0:3]
	s_waitcnt lgkmcnt(1)
	v_mfma_f32_16x16x32_bf16 v[10:13], v[58:61], v[50:53], v[10:13]
	ds_read_b128 v[46:49], v22 offset:640
	ds_read_b128 v[50:53], v22 offset:704
	ds_read_b128 v[54:57], v23 offset:704
	s_waitcnt lgkmcnt(2)
	v_mfma_f32_16x16x32_bf16 v[0:3], v[14:17], v[46:49], v[0:3]
	ds_read_b128 v[14:17], v23 offset:17280
	ds_read_b128 v[58:61], v23 offset:17344
	s_waitcnt lgkmcnt(1)
	v_mfma_f32_16x16x32_bf16 v[10:13], v[14:17], v[46:49], v[10:13]
	ds_read_b128 v[14:17], v23 offset:768
	v_mfma_f32_16x16x32_bf16 v[0:3], v[54:57], v[50:53], v[0:3]
	s_waitcnt lgkmcnt(1)
	v_mfma_f32_16x16x32_bf16 v[10:13], v[58:61], v[50:53], v[10:13]
	ds_read_b128 v[46:49], v22 offset:768
	ds_read_b128 v[50:53], v22 offset:832
	ds_read_b128 v[54:57], v23 offset:832
	s_waitcnt lgkmcnt(2)
	v_mfma_f32_16x16x32_bf16 v[0:3], v[14:17], v[46:49], v[0:3]
	ds_read_b128 v[14:17], v23 offset:17408
	ds_read_b128 v[58:61], v23 offset:17472
	s_waitcnt lgkmcnt(1)
	v_mfma_f32_16x16x32_bf16 v[10:13], v[14:17], v[46:49], v[10:13]
	ds_read_b128 v[14:17], v23 offset:896
	v_mfma_f32_16x16x32_bf16 v[0:3], v[54:57], v[50:53], v[0:3]
	s_waitcnt lgkmcnt(1)
	v_mfma_f32_16x16x32_bf16 v[10:13], v[58:61], v[50:53], v[10:13]
	ds_read_b128 v[46:49], v22 offset:896
	ds_read_b128 v[50:53], v22 offset:960
	ds_read_b128 v[54:57], v23 offset:960
	s_waitcnt lgkmcnt(2)
	v_mfma_f32_16x16x32_bf16 v[0:3], v[14:17], v[46:49], v[0:3]
	ds_read_b128 v[14:17], v23 offset:17536
	ds_read_b128 v[58:61], v23 offset:17600
	s_waitcnt lgkmcnt(0)
	s_barrier
	v_mfma_f32_16x16x32_bf16 v[10:13], v[14:17], v[46:49], v[10:13]
	v_mfma_f32_16x16x32_bf16 v[14:17], v[54:57], v[50:53], v[0:3]
	v_mfma_f32_16x16x32_bf16 v[0:3], v[58:61], v[50:53], v[10:13]
	s_nop 5
	v_or_b32_e32 v12, s1, v21
	v_add_u32_e32 v13, s0, v20
	s_ashr_i32 s0, s34, 5
	v_lshlrev_b32_e32 v4, 9, v12
	v_or_b32_e32 v46, v13, v45
	s_and_b32 s35, s0, -4
	v_lshl_add_u64 v[10:11], s[8:9], 0, v[4:5]
	v_add_u32_e32 v4, 0xfffffc00, v46
	v_cmp_lt_u32_e64 s[0:1], s33, v13
	v_cmp_gt_u32_e32 vcc, s31, v13
	v_cvt_pk_bf16_f32 v14, v14, v15
	v_cndmask_b32_e64 v4, v46, v4, s[0:1]
	v_ashrrev_i32_e32 v13, 8, v4
	v_cvt_pk_bf16_f32 v15, v16, v17
	v_add_u32_e32 v16, s35, v13
	v_and_b32_e32 v47, 0xec, v4
	v_ashrrev_i32_e32 v17, 31, v16
	s_and_saveexec_b64 s[26:27], vcc
	s_xor_b64 s[26:27], exec, s[26:27]
	s_cbranch_execz .LBB0_285
	v_lshlrev_b64 v[16:17], 17, v[16:17]
	v_lshl_add_u64 v[16:17], v[10:11], 0, v[16:17]
	v_lshlrev_b32_e32 v4, 1, v47
	v_lshl_add_u64 v[16:17], v[16:17], 0, v[4:5]
	global_store_dwordx2 v[16:17], v[14:15], off

; #define LAS __attribute__((address_space(3)))
; #define LDS_WAIT() asm volatile("s_waitcnt lgkmcnt(0)" ::: "memory")
; __device__ __forceinline__ unsigned pk2(float lo, float hi) { return pg8::cvt_pk_bf16(lo, hi); }
; __device__ __forceinline__ void wt_store16(const WsRef& w, const void* p, u32x4 v) { __builtin_amdgcn_raw_buffer_store_b128(v, w.r, (unsigned)((const unsigned char*)p - w.base), 0, 16); }
; __device__ __forceinline__ void p0_transpose_item64(const WsRef& wsr, const float* W, int K, int N, bf16* WT, LAS float* scr, int item, int lane, const float* kscale = nullptr) {
;     const int nblk = N / 64, kb = item / nblk, nb = item % nblk, k0 = 64 * kb, n0 = 64 * nb;
;     const int kq = lane >> 4, nq = lane & 15;
;     f32x4 v[16];
; #pragma unroll
;     for (int i = 0; i < 16; ++i) v[i] = *(const f32x4*)(W + (size_t)(k0 + 4 * i + kq) * N + n0 + nq * 4);
; #pragma unroll
;     for (int i = 0; i < 16; ++i) { const int kk = 4 * i + kq; const float sc = kscale ? kscale[k0 + kk] : 1.0f; LAS float* d = scr + kk * 65 + nq * 4;
;         d[0] = v[i][0] * sc; d[1] = v[i][1] * sc; d[2] = v[i][2] * sc; d[3] = v[i][3] * sc; }
;     LDS_WAIT(); asm volatile("" ::: "memory");
;     const int c = lane & 7;
; #pragma unroll
;     for (int j = 0; j < 8; ++j) { const int n = (lane >> 3) + 8 * j; const LAS float* s = scr + (8 * c) * 65 + n;
;         u32x4 o; o.x = pk2(s[0 * 65], s[1 * 65]); o.y = pk2(s[2 * 65], s[3 * 65]); o.z = pk2(s[4 * 65], s[5 * 65]); o.w = pk2(s[6 * 65], s[7 * 65]);
;         wt_store16(wsr, WT + (size_t)(n0 + n) * K + k0 + 8 * c, o); }
; __global__ void __launch_bounds__(512, 2) fwd_mega(Args a) {
;     ...
;             for (int it = sb * 8 + wave; it < NIT3; it += sG * 8) { int r = it;
;                 if (r < I_SQ) { p0_transpose_item64(wsr, a.in[13], D, D, WOUT, scr, r, lane); continue; } r -= I_SQ;
;                 if (r < I_SQ) { p0_transpose_item64(wsr, a.in[16], D, D, WXQ, scr, r, lane, a.in[14]); continue; } r -= I_SQ;
;                 if (r < I_SQ) { p0_transpose_item64(wsr, a.in[18], D, D, WXO, scr, r, lane); continue; } r -= I_SQ;
;                 if (r < I_F1) { p0_transpose_item64(wsr, a.in[20], D, FF, WFF1, scr, r, lane, a.in[19]); continue; } r -= I_F1;
;                 p0_transpose_item64(wsr, a.in[21], FF, D, WFF2, scr, r, lane); }
.LBB0_295:
	s_cmpk_gt_i32 s34, 0xff
	s_mov_b64 s[0:1], -1
	s_cbranch_scc0 .LBB0_357
	s_cmpk_gt_u32 s34, 0x1ff
	s_cbranch_scc0 .LBB0_330
	s_cmpk_gt_u32 s34, 0x2ff
	s_cbranch_scc0 .LBB0_327
	s_cmpk_gt_u32 s34, 0x6ff
	s_cbranch_scc0 .LBB0_300
	s_add_i32 s0, s31, 0x3e400
	s_and_b32 s1, s0, 0x3ffc0
	s_and_b32 s0, s3, 0x3c0
	v_or_b32_e32 v2, s1, v86
	s_lshl_b32 s8, s0, 2
	v_lshl_add_u64 v[0:1], v[66:67], 0, s[8:9]
	v_lshlrev_b32_e32 v64, 12, v2
	v_lshl_add_u64 v[60:61], v[0:1], 0, v[64:65]
	v_add_co_u32_e32 v4, vcc, 0x4000, v60
	s_mov_b32 s88, s84
	s_nop 0
	v_addc_co_u32_e32 v5, vcc, 0, v61, vcc
	v_add_co_u32_e32 v8, vcc, 0x8000, v60
	global_load_dwordx4 v[0:3], v[60:61], off nt
	s_nop 0
	global_load_dwordx4 v[4:7], v[4:5], off nt
	v_addc_co_u32_e32 v9, vcc, 0, v61, vcc
	v_add_co_u32_e32 v12, vcc, 0xc000, v60
	s_nop 1
	v_addc_co_u32_e32 v13, vcc, 0, v61, vcc
	v_add_co_u32_e32 v16, vcc, 0x10000, v60
	global_load_dwordx4 v[8:11], v[8:9], off nt
	s_nop 0
	global_load_dwordx4 v[12:15], v[12:13], off nt
	v_addc_co_u32_e32 v17, vcc, 0, v61, vcc
	v_add_co_u32_e32 v20, vcc, 0x14000, v60
	s_nop 1
	v_addc_co_u32_e32 v21, vcc, 0, v61, vcc
	v_add_co_u32_e32 v24, vcc, 0x18000, v60
	global_load_dwordx4 v[16:19], v[16:17], off nt
	s_nop 0
	global_load_dwordx4 v[20:23], v[20:21], off nt
	v_addc_co_u32_e32 v25, vcc, 0, v61, vcc
	v_add_co_u32_e32 v28, vcc, 0x1c000, v60
	s_nop 1
	v_addc_co_u32_e32 v29, vcc, 0, v61, vcc
	global_load_dwordx4 v[24:27], v[24:25], off nt
	s_nop 0
	global_load_dwordx4 v[28:31], v[28:29], off nt
	v_add_co_u32_e32 v32, vcc, 0x20000, v60
	s_nop 1
	v_addc_co_u32_e32 v33, vcc, 0, v61, vcc
	v_add_co_u32_e32 v36, vcc, 0x24000, v60
	s_nop 1
	v_addc_co_u32_e32 v37, vcc, 0, v61, vcc
	global_load_dwordx4 v[32:35], v[32:33], off nt
	s_nop 0
	global_load_dwordx4 v[36:39], v[36:37], off nt
	v_add_co_u32_e32 v40, vcc, 0x28000, v60
	s_nop 1
	v_addc_co_u32_e32 v41, vcc, 0, v61, vcc
	v_add_co_u32_e32 v44, vcc, 0x2c000, v60
	s_nop 1
	v_addc_co_u32_e32 v45, vcc, 0, v61, vcc
	global_load_dwordx4 v[40:43], v[40:41], off nt
	s_nop 0
	global_load_dwordx4 v[44:47], v[44:45], off nt
	v_add_co_u32_e32 v48, vcc, 0x30000, v60
	s_nop 1
	v_addc_co_u32_e32 v49, vcc, 0, v61, vcc
	v_add_co_u32_e32 v52, vcc, 0x34000, v60
	s_nop 1
	v_addc_co_u32_e32 v53, vcc, 0, v61, vcc
	global_load_dwordx4 v[48:51], v[48:49], off nt
	s_nop 0
	global_load_dwordx4 v[52:55], v[52:53], off nt
	v_add_co_u32_e32 v56, vcc, 0x38000, v60
	s_nop 1
	v_addc_co_u32_e32 v57, vcc, 0, v61, vcc
	global_load_dwordx4 v[56:59], v[56:57], off nt
	v_add_co_u32_e32 v60, vcc, 0x3c000, v60
	s_nop 1
	v_addc_co_u32_e32 v61, vcc, 0, v61, vcc
	global_load_dwordx4 v[60:63], v[60:61], off nt
	s_waitcnt vmcnt(0)
	ds_write2_b32 v88, v0, v1 offset1:1
	ds_write2_b32 v88, v2, v3 offset0:2 offset1:3
	ds_write2_b32 v73, v4, v5 offset1:1
	ds_write2_b32 v77, v6, v7 offset1:1
	ds_write2_b32 v81, v8, v9 offset1:1
	ds_write2_b32 v85, v10, v11 offset1:1
	ds_write2_b32 v107, v12, v13 offset1:1
	ds_write2_b32 v108, v14, v15 offset1:1
	ds_write2_b32 v109, v16, v17 offset1:1
	ds_write2_b32 v110, v18, v19 offset1:1
	ds_write2_b32 v111, v20, v21 offset1:1
	ds_write2_b32 v112, v22, v23 offset1:1
	v_add_u32_e32 v0, 0x1860, v88
	v_add_u32_e32 v20, 0x400, v69
	v_lshl_add_u32 v21, s1, 1, v68
	ds_write2_b32 v0, v24, v25 offset1:1
	v_add_u32_e32 v0, 0x1868, v88
	ds_write2_b32 v0, v26, v27 offset1:1
	v_add_u32_e32 v0, 0x1c70, v88
	ds_write2_b32 v0, v28, v29 offset1:1
	v_add_u32_e32 v0, 0x1c78, v88
	ds_write2_b32 v0, v30, v31 offset1:1
	v_add_u32_e32 v0, 0x2080, v88
	ds_write2_b32 v0, v32, v33 offset1:1
	v_add_u32_e32 v0, 0x2088, v88
	ds_write2_b32 v0, v34, v35 offset1:1
	v_add_u32_e32 v0, 0x2490, v88
	ds_write2_b32 v0, v36, v37 offset1:1
	v_add_u32_e32 v0, 0x2498, v88
	ds_write2_b32 v0, v38, v39 offset1:1
	v_add_u32_e32 v0, 0x28a0, v88
	ds_write2_b32 v0, v40, v41 offset1:1
	v_add_u32_e32 v0, 0x28a8, v88
	ds_write2_b32 v0, v42, v43 offset1:1
	v_add_u32_e32 v0, 0x2cb0, v88
	ds_write2_b32 v0, v44, v45 offset1:1
	v_add_u32_e32 v0, 0x2cb8, v88
	ds_write2_b32 v0, v46, v47 offset1:1
	v_add_u32_e32 v0, 0x30c0, v88
	ds_write2_b32 v0, v48, v49 offset1:1
	v_add_u32_e32 v0, 0x30c8, v88
	ds_write2_b32 v0, v50, v51 offset1:1
	v_add_u32_e32 v0, 0x34d0, v88
	ds_write2_b32 v0, v52, v53 offset1:1
	v_add_u32_e32 v0, 0x34d8, v88
	ds_write2_b32 v0, v54, v55 offset1:1
	v_add_u32_e32 v0, 0x38e0, v88
	ds_write2_b32 v0, v56, v57 offset1:1
	v_add_u32_e32 v0, 0x38e8, v88
	ds_write2_b32 v0, v58, v59 offset1:1
	v_add_u32_e32 v0, 0x3cf0, v88
	ds_write2_b32 v0, v60, v61 offset1:1
	v_add_u32_e32 v0, 0x3cf8, v88
	ds_write2_b32 v0, v62, v63 offset1:1
	s_waitcnt lgkmcnt(0)
	ds_read2_b32 v[4:5], v69 offset1:8
	ds_read2_b32 v[6:7], v69 offset0:65 offset1:73
	ds_read2_b32 v[8:9], v69 offset0:130 offset1:138
	ds_read2_b32 v[10:11], v69 offset0:195 offset1:203
	ds_read2_b32 v[12:13], v20 offset0:4 offset1:12
	ds_read2_b32 v[14:15], v20 offset0:69 offset1:77
	ds_read2_b32 v[16:17], v20 offset0:134 offset1:142
	ds_read2_b32 v[18:19], v20 offset0:199 offset1:207
	s_waitcnt lgkmcnt(6)
	v_cvt_pk_bf16_f32 v0, v4, v6
	v_or_b32_e32 v4, s0, v89
	v_lshl_add_u32 v4, v4, 13, v21
	s_waitcnt lgkmcnt(4)
	v_cvt_pk_bf16_f32 v1, v8, v10
	s_waitcnt lgkmcnt(2)
	v_cvt_pk_bf16_f32 v2, v12, v14
	s_waitcnt lgkmcnt(0)
; #define LAS __attribute__((address_space(3)))
; __device__ __forceinline__ unsigned pk2(float lo, float hi) { return pg8::cvt_pk_bf16(lo, hi); }
; __device__ __forceinline__ void wt_store16(const WsRef& w, const void* p, u32x4 v) { __builtin_amdgcn_raw_buffer_store_b128(v, w.r, (unsigned)((const unsigned char*)p - w.base), 0, 16); }
; __device__ __forceinline__ void p0_transpose_item64(const WsRef& wsr, const float* W, int K, int N, bf16* WT, LAS float* scr, int item, int lane, const float* kscale = nullptr) {
;     ...
;     f32x4 v[16];
; #pragma unroll
;     for (int i = 0; i < 16; ++i) v[i] = *(const f32x4*)(W + (size_t)(k0 + 4 * i + kq) * N + n0 + nq * 4);
; #pragma unroll
;     for (int i = 0; i < 16; ++i) { const int kk = 4 * i + kq; const float sc = kscale ? kscale[k0 + kk] : 1.0f; LAS float* d = scr + kk * 65 + nq * 4;
;         d[0] = v[i][0] * sc; d[1] = v[i][1] * sc; d[2] = v[i][2] * sc; d[3] = v[i][3] * sc; }
;     ...
;     for (int j = 0; j < 8; ++j) { const int n = (lane >> 3) + 8 * j; const LAS float* s = scr + (8 * c) * 65 + n;
;         u32x4 o; o.x = pk2(s[0 * 65], s[1 * 65]); o.y = pk2(s[2 * 65], s[3 * 65]); o.z = pk2(s[4 * 65], s[5 * 65]); o.w = pk2(s[6 * 65], s[7 * 65]);
;         wt_store16(wsr, WT + (size_t)(n0 + n) * K + k0 + 8 * c, o); }
	v_cvt_pk_bf16_f32 v3, v16, v18
	v_subrev_u32_e32 v4, s84, v4
	buffer_store_dwordx4 v[0:3], v4, s[88:91], 0 offen sc1
	v_or_b32_e32 v4, s0, v90
	v_lshl_add_u32 v4, v4, 13, v21
	v_cvt_pk_bf16_f32 v0, v5, v7
	v_cvt_pk_bf16_f32 v1, v9, v11
	v_cvt_pk_bf16_f32 v2, v13, v15
	v_cvt_pk_bf16_f32 v3, v17, v19
	v_subrev_u32_e32 v22, s84, v4
	ds_read2_b32 v[4:5], v69 offset0:16 offset1:24
	ds_read2_b32 v[6:7], v69 offset0:81 offset1:89
	ds_read2_b32 v[8:9], v69 offset0:146 offset1:154
	ds_read2_b32 v[10:11], v69 offset0:211 offset1:219
	ds_read2_b32 v[12:13], v20 offset0:20 offset1:28
	ds_read2_b32 v[14:15], v20 offset0:85 offset1:93
	ds_read2_b32 v[16:17], v20 offset0:150 offset1:158
	ds_read2_b32 v[18:19], v20 offset0:215 offset1:223
	buffer_store_dwordx4 v[0:3], v22, s[88:91], 0 offen sc1
	s_waitcnt lgkmcnt(6)
	s_nop 0
	v_cvt_pk_bf16_f32 v0, v4, v6
	v_or_b32_e32 v4, s0, v91
	v_lshl_add_u32 v4, v4, 13, v21
	s_waitcnt lgkmcnt(4)
	v_cvt_pk_bf16_f32 v1, v8, v10
	s_waitcnt lgkmcnt(2)
	v_cvt_pk_bf16_f32 v2, v12, v14
	s_waitcnt lgkmcnt(0)
	v_cvt_pk_bf16_f32 v3, v16, v18
	v_subrev_u32_e32 v4, s84, v4
	buffer_store_dwordx4 v[0:3], v4, s[88:91], 0 offen sc1
	v_or_b32_e32 v4, s0, v92
	v_lshl_add_u32 v4, v4, 13, v21
	v_cvt_pk_bf16_f32 v0, v5, v7
	v_cvt_pk_bf16_f32 v1, v9, v11
	v_cvt_pk_bf16_f32 v2, v13, v15
	v_cvt_pk_bf16_f32 v3, v17, v19
	v_subrev_u32_e32 v22, s84, v4
	ds_read2_b32 v[4:5], v69 offset0:32 offset1:40
	ds_read2_b32 v[6:7], v69 offset0:97 offset1:105
	ds_read2_b32 v[8:9], v69 offset0:162 offset1:170
	ds_read2_b32 v[10:11], v69 offset0:227 offset1:235
	ds_read2_b32 v[12:13], v20 offset0:36 offset1:44
	ds_read2_b32 v[14:15], v20 offset0:101 offset1:109
	ds_read2_b32 v[16:17], v20 offset0:166 offset1:174
	ds_read2_b32 v[18:19], v20 offset0:231 offset1:239
	buffer_store_dwordx4 v[0:3], v22, s[88:91], 0 offen sc1
	s_waitcnt lgkmcnt(6)
	s_nop 0
	v_cvt_pk_bf16_f32 v0, v4, v6
	v_or_b32_e32 v4, s0, v93
	v_lshl_add_u32 v4, v4, 13, v21
	s_waitcnt lgkmcnt(4)
	v_cvt_pk_bf16_f32 v1, v8, v10
	s_waitcnt lgkmcnt(2)
	v_cvt_pk_bf16_f32 v2, v12, v14
	s_waitcnt lgkmcnt(0)
	v_cvt_pk_bf16_f32 v3, v16, v18
	v_subrev_u32_e32 v4, s84, v4
	buffer_store_dwordx4 v[0:3], v4, s[88:91], 0 offen sc1
	v_or_b32_e32 v4, s0, v94
	v_lshl_add_u32 v4, v4, 13, v21
	v_cvt_pk_bf16_f32 v0, v5, v7
	v_cvt_pk_bf16_f32 v1, v9, v11
	v_cvt_pk_bf16_f32 v2, v13, v15
	v_cvt_pk_bf16_f32 v3, v17, v19
	v_subrev_u32_e32 v22, s84, v4
	ds_read2_b32 v[4:5], v69 offset0:48 offset1:56
	ds_read2_b32 v[6:7], v69 offset0:113 offset1:121
	ds_read2_b32 v[8:9], v69 offset0:178 offset1:186
	ds_read2_b32 v[10:11], v69 offset0:243 offset1:251
	ds_read2_b32 v[12:13], v20 offset0:52 offset1:60
	ds_read2_b32 v[14:15], v20 offset0:117 offset1:125
	ds_read2_b32 v[16:17], v20 offset0:182 offset1:190
	ds_read2_b32 v[18:19], v20 offset0:247 offset1:255
	buffer_store_dwordx4 v[0:3], v22, s[88:91], 0 offen sc1
	s_waitcnt lgkmcnt(6)
	s_nop 0
	v_cvt_pk_bf16_f32 v0, v4, v6
	v_or_b32_e32 v4, s0, v95
	v_lshl_add_u32 v4, v4, 13, v21
	s_waitcnt lgkmcnt(4)
	v_cvt_pk_bf16_f32 v1, v8, v10
	s_waitcnt lgkmcnt(2)
	v_cvt_pk_bf16_f32 v2, v12, v14
	s_waitcnt lgkmcnt(0)
	v_cvt_pk_bf16_f32 v3, v16, v18
	v_subrev_u32_e32 v4, s84, v4
	buffer_store_dwordx4 v[0:3], v4, s[88:91], 0 offen sc1
	v_or_b32_e32 v4, s0, v96
	v_lshl_add_u32 v4, v4, 13, v21
	v_cvt_pk_bf16_f32 v0, v5, v7
	v_cvt_pk_bf16_f32 v1, v9, v11
	v_cvt_pk_bf16_f32 v2, v13, v15
	v_cvt_pk_bf16_f32 v3, v17, v19
	v_subrev_u32_e32 v4, s84, v4
	buffer_store_dwordx4 v[0:3], v4, s[88:91], 0 offen sc1
	s_waitcnt lgkmcnt(0)
	s_mov_b64 s[0:1], 0
.LBB0_300:
	s_andn2_b64 vcc, exec, s[0:1]
	s_cbranch_vccnz .LBB0_326
	s_add_i32 s0, s34, 0xfd00
	s_and_b32 s38, s0, 0xffc0
	s_and_b32 s35, s3, 0xfc0
	v_or_b32_e32 v114, s38, v86
	s_lshl_b32 s8, s35, 2
	v_lshl_add_u64 v[0:1], v[70:71], 0, s[8:9]
	v_lshlrev_b32_e32 v64, 14, v114
	v_lshl_add_u64 v[0:1], v[0:1], 0, v[64:65]
	v_add_co_u32_e32 v2, vcc, 0x10000, v0
	v_cndmask_b32_e64 v64, 0, 1, s[10:11]
	s_nop 0
	v_addc_co_u32_e32 v3, vcc, 0, v1, vcc
	global_load_dwordx4 v[60:63], v[0:1], off nt
	global_load_dwordx4 v[56:59], v[2:3], off nt
	v_add_co_u32_e32 v2, vcc, 0x20000, v0
	v_cmp_ne_u32_e64 s[0:1], 1, v64
	s_nop 0
	v_addc_co_u32_e32 v3, vcc, 0, v1, vcc
	v_add_co_u32_e32 v4, vcc, 0x30000, v0
	v_add_lshl_u32 v113, s38, v86, 2
	s_nop 0
	v_addc_co_u32_e32 v5, vcc, 0, v1, vcc
	global_load_dwordx4 v[52:55], v[2:3], off nt
	global_load_dwordx4 v[48:51], v[4:5], off nt
	v_add_co_u32_e32 v2, vcc, 0x40000, v0
	s_nop 1
	v_addc_co_u32_e32 v3, vcc, 0, v1, vcc
	v_add_co_u32_e32 v4, vcc, 0x50000, v0
	s_nop 1
	v_addc_co_u32_e32 v5, vcc, 0, v1, vcc
	global_load_dwordx4 v[44:47], v[2:3], off nt
	global_load_dwordx4 v[40:43], v[4:5], off nt
	v_add_co_u32_e32 v2, vcc, 0x60000, v0
	s_nop 1
	v_addc_co_u32_e32 v3, vcc, 0, v1, vcc
	v_add_co_u32_e32 v4, vcc, 0x70000, v0
	s_nop 1
	v_addc_co_u32_e32 v5, vcc, 0, v1, vcc
	global_load_dwordx4 v[36:39], v[2:3], off nt
	global_load_dwordx4 v[32:35], v[4:5], off nt
	v_add_co_u32_e32 v2, vcc, 0x80000, v0
	s_nop 1
	v_addc_co_u32_e32 v3, vcc, 0, v1, vcc
	v_add_co_u32_e32 v4, vcc, 0x90000, v0
	s_nop 1
	v_addc_co_u32_e32 v5, vcc, 0, v1, vcc
	global_load_dwordx4 v[28:31], v[2:3], off nt
	global_load_dwordx4 v[24:27], v[4:5], off nt
	v_add_co_u32_e32 v2, vcc, 0xa0000, v0
	s_nop 1
	v_addc_co_u32_e32 v3, vcc, 0, v1, vcc
	v_add_co_u32_e32 v4, vcc, 0xb0000, v0
	s_nop 1
	v_addc_co_u32_e32 v5, vcc, 0, v1, vcc
	global_load_dwordx4 v[20:23], v[2:3], off nt
	global_load_dwordx4 v[16:19], v[4:5], off nt
	v_add_co_u32_e32 v2, vcc, 0xc0000, v0
	s_nop 1
	v_addc_co_u32_e32 v3, vcc, 0, v1, vcc
	v_add_co_u32_e32 v4, vcc, 0xd0000, v0
	s_nop 1
	v_addc_co_u32_e32 v5, vcc, 0, v1, vcc
	global_load_dwordx4 v[12:15], v[2:3], off nt
	global_load_dwordx4 v[8:11], v[4:5], off nt
	v_add_co_u32_e32 v2, vcc, 0xe0000, v0
	s_nop 1
	v_addc_co_u32_e32 v3, vcc, 0, v1, vcc
	v_add_co_u32_e32 v0, vcc, 0xf0000, v0
	s_nop 1
	v_addc_co_u32_e32 v1, vcc, 0, v1, vcc
	global_load_dwordx4 v[4:7], v[2:3], off nt
	s_nop 0
	global_load_dwordx4 v[0:3], v[0:1], off nt
	s_andn2_b64 vcc, exec, s[10:11]
	s_cbranch_vccnz .LBB0_367
	v_readlane_b32 s52, v255, 10
	v_lshlrev_b32_e32 v64, 2, v114
	v_readlane_b32 s58, v255, 16
	v_readlane_b32 s59, v255, 17
	s_nop 4
	global_load_dword v114, v64, s[58:59] nt
	s_nop 0
	global_load_dword v64, v113, s[58:59] offset:16 nt
	v_readlane_b32 s53, v255, 11
	v_readlane_b32 s54, v255, 12
	v_readlane_b32 s55, v255, 13
	v_readlane_b32 s56, v255, 14
	v_readlane_b32 s57, v255, 15
	v_readlane_b32 s60, v255, 18
	v_readlane_b32 s61, v255, 19
	v_readlane_b32 s62, v255, 20
	v_readlane_b32 s63, v255, 21
	v_readlane_b32 s64, v255, 22
	v_readlane_b32 s65, v255, 23
	v_readlane_b32 s66, v255, 24
	v_readlane_b32 s67, v255, 25
	s_waitcnt vmcnt(0)
	v_pk_mul_f32 v[116:117], v[60:61], v[114:115] op_sel_hi:[1,0]
	v_pk_mul_f32 v[114:115], v[62:63], v[114:115] op_sel_hi:[1,0]
	ds_write2_b32 v88, v116, v117 offset1:1
	ds_write2_b32 v88, v114, v115 offset0:2 offset1:3
	s_cbranch_execnz .LBB0_304

; #define LAS __attribute__((address_space(3)))
; __device__ __forceinline__ void p0_transpose_item64(const WsRef& wsr, const float* W, int K, int N, bf16* WT, LAS float* scr, int item, int lane, const float* kscale = nullptr) {
;     ...
;     for (int i = 0; i < 16; ++i) { const int kk = 4 * i + kq; const float sc = kscale ? kscale[k0 + kk] : 1.0f; LAS float* d = scr + kk * 65 + nq * 4;
;         d[0] = v[i][0] * sc; d[1] = v[i][1] * sc; d[2] = v[i][2] * sc; d[3] = v[i][3] * sc; }
.LBB0_304:
	s_waitcnt vmcnt(0)
	v_pk_mul_f32 v[56:57], v[56:57], v[64:65] op_sel_hi:[1,0]
	v_add_u32_e32 v60, v87, v97
	ds_write2_b32 v60, v56, v57 offset1:1
	v_pk_mul_f32 v[56:57], v[58:59], v[64:65] op_sel_hi:[1,0]
	s_and_b64 vcc, exec, s[0:1]
	ds_write2_b32 v60, v56, v57 offset0:2 offset1:3
	s_cbranch_vccnz .LBB0_368
	v_readlane_b32 s52, v255, 10
	v_readlane_b32 s58, v255, 16
	v_readlane_b32 s59, v255, 17
	s_nop 4
	global_load_dword v58, v113, s[58:59] offset:32 nt
	global_load_dword v56, v113, s[58:59] offset:48 nt
	v_add_u32_e32 v57, v87, v98
	v_readlane_b32 s53, v255, 11
	v_readlane_b32 s54, v255, 12
	v_readlane_b32 s55, v255, 13
	v_readlane_b32 s56, v255, 14
	v_readlane_b32 s57, v255, 15
	v_readlane_b32 s60, v255, 18
	v_readlane_b32 s61, v255, 19
	v_readlane_b32 s62, v255, 20
	v_readlane_b32 s63, v255, 21
	v_readlane_b32 s64, v255, 22
	v_readlane_b32 s65, v255, 23
	v_readlane_b32 s66, v255, 24
	v_readlane_b32 s67, v255, 25
	s_waitcnt vmcnt(1)
	v_pk_mul_f32 v[60:61], v[52:53], v[58:59] op_sel_hi:[1,0]
	v_pk_mul_f32 v[58:59], v[54:55], v[58:59] op_sel_hi:[1,0]
	ds_write2_b32 v57, v60, v61 offset1:1
	ds_write2_b32 v57, v58, v59 offset0:2 offset1:3
	s_cbranch_execnz .LBB0_307

; #define LAS __attribute__((address_space(3)))
; __device__ __forceinline__ void p0_transpose_item64(const WsRef& wsr, const float* W, int K, int N, bf16* WT, LAS float* scr, int item, int lane, const float* kscale = nullptr) {
;     ...
;     for (int i = 0; i < 16; ++i) { const int kk = 4 * i + kq; const float sc = kscale ? kscale[k0 + kk] : 1.0f; LAS float* d = scr + kk * 65 + nq * 4;
;         d[0] = v[i][0] * sc; d[1] = v[i][1] * sc; d[2] = v[i][2] * sc; d[3] = v[i][3] * sc; }
.LBB0_307:
	s_waitcnt vmcnt(0)
	v_pk_mul_f32 v[48:49], v[48:49], v[56:57] op_sel_hi:[1,0]
	v_add_u32_e32 v52, v87, v99
	ds_write2_b32 v52, v48, v49 offset1:1
	v_pk_mul_f32 v[48:49], v[50:51], v[56:57] op_sel_hi:[1,0]
	s_and_b64 vcc, exec, s[0:1]
	ds_write2_b32 v52, v48, v49 offset0:2 offset1:3
	s_cbranch_vccnz .LBB0_369
	v_readlane_b32 s52, v255, 10
	v_readlane_b32 s58, v255, 16
	v_readlane_b32 s59, v255, 17
	s_nop 4
	global_load_dword v50, v113, s[58:59] offset:64 nt
	global_load_dword v48, v113, s[58:59] offset:80 nt
	v_add_u32_e32 v49, v87, v100
	v_readlane_b32 s53, v255, 11
	v_readlane_b32 s54, v255, 12
	v_readlane_b32 s55, v255, 13
	v_readlane_b32 s56, v255, 14
	v_readlane_b32 s57, v255, 15
	v_readlane_b32 s60, v255, 18
	v_readlane_b32 s61, v255, 19
	v_readlane_b32 s62, v255, 20
	v_readlane_b32 s63, v255, 21
	v_readlane_b32 s64, v255, 22
	v_readlane_b32 s65, v255, 23
	v_readlane_b32 s66, v255, 24
	v_readlane_b32 s67, v255, 25
	s_waitcnt vmcnt(1)
	v_pk_mul_f32 v[52:53], v[44:45], v[50:51] op_sel_hi:[1,0]
	v_pk_mul_f32 v[50:51], v[46:47], v[50:51] op_sel_hi:[1,0]
	ds_write2_b32 v49, v52, v53 offset1:1
	ds_write2_b32 v49, v50, v51 offset0:2 offset1:3
	s_cbranch_execnz .LBB0_310

; #define LAS __attribute__((address_space(3)))
; __device__ __forceinline__ void p0_transpose_item64(const WsRef& wsr, const float* W, int K, int N, bf16* WT, LAS float* scr, int item, int lane, const float* kscale = nullptr) {
;     ...
;     for (int i = 0; i < 16; ++i) { const int kk = 4 * i + kq; const float sc = kscale ? kscale[k0 + kk] : 1.0f; LAS float* d = scr + kk * 65 + nq * 4;
;         d[0] = v[i][0] * sc; d[1] = v[i][1] * sc; d[2] = v[i][2] * sc; d[3] = v[i][3] * sc; }
.LBB0_310:
	s_waitcnt vmcnt(0)
	v_pk_mul_f32 v[40:41], v[40:41], v[48:49] op_sel_hi:[1,0]
	v_add_u32_e32 v44, v87, v101
	ds_write2_b32 v44, v40, v41 offset1:1
	v_pk_mul_f32 v[40:41], v[42:43], v[48:49] op_sel_hi:[1,0]
	s_and_b64 vcc, exec, s[0:1]
	ds_write2_b32 v44, v40, v41 offset0:2 offset1:3
	s_cbranch_vccnz .LBB0_370
	v_readlane_b32 s52, v255, 10
	v_readlane_b32 s58, v255, 16
	v_readlane_b32 s59, v255, 17
	s_nop 4
	global_load_dword v42, v113, s[58:59] offset:96 nt
	global_load_dword v40, v113, s[58:59] offset:112 nt
	v_add_u32_e32 v41, v87, v102
	v_readlane_b32 s53, v255, 11
	v_readlane_b32 s54, v255, 12
	v_readlane_b32 s55, v255, 13
	v_readlane_b32 s56, v255, 14
	v_readlane_b32 s57, v255, 15
	v_readlane_b32 s60, v255, 18
	v_readlane_b32 s61, v255, 19
	v_readlane_b32 s62, v255, 20
	v_readlane_b32 s63, v255, 21
	v_readlane_b32 s64, v255, 22
	v_readlane_b32 s65, v255, 23
	v_readlane_b32 s66, v255, 24
	v_readlane_b32 s67, v255, 25
	s_waitcnt vmcnt(1)
	v_pk_mul_f32 v[44:45], v[36:37], v[42:43] op_sel_hi:[1,0]
	v_pk_mul_f32 v[42:43], v[38:39], v[42:43] op_sel_hi:[1,0]
	ds_write2_b32 v41, v44, v45 offset1:1
	ds_write2_b32 v41, v42, v43 offset0:2 offset1:3
	s_cbranch_execnz .LBB0_313

; #define LAS __attribute__((address_space(3)))
; __device__ __forceinline__ void p0_transpose_item64(const WsRef& wsr, const float* W, int K, int N, bf16* WT, LAS float* scr, int item, int lane, const float* kscale = nullptr) {
;     ...
;     for (int i = 0; i < 16; ++i) { const int kk = 4 * i + kq; const float sc = kscale ? kscale[k0 + kk] : 1.0f; LAS float* d = scr + kk * 65 + nq * 4;
;         d[0] = v[i][0] * sc; d[1] = v[i][1] * sc; d[2] = v[i][2] * sc; d[3] = v[i][3] * sc; }
.LBB0_313:
	s_waitcnt vmcnt(0)
	v_pk_mul_f32 v[32:33], v[32:33], v[40:41] op_sel_hi:[1,0]
	v_add_u32_e32 v36, v87, v103
	ds_write2_b32 v36, v32, v33 offset1:1
	v_pk_mul_f32 v[32:33], v[34:35], v[40:41] op_sel_hi:[1,0]
	s_and_b64 vcc, exec, s[0:1]
	ds_write2_b32 v36, v32, v33 offset0:2 offset1:3
	s_cbranch_vccnz .LBB0_371
	v_readlane_b32 s52, v255, 10
	v_readlane_b32 s58, v255, 16
	v_readlane_b32 s59, v255, 17
	s_nop 4
	global_load_dword v34, v113, s[58:59] offset:128 nt
	global_load_dword v32, v113, s[58:59] offset:144 nt
	v_add_u32_e32 v33, v87, v104
	v_readlane_b32 s53, v255, 11
	v_readlane_b32 s54, v255, 12
	v_readlane_b32 s55, v255, 13
	v_readlane_b32 s56, v255, 14
	v_readlane_b32 s57, v255, 15
	v_readlane_b32 s60, v255, 18
	v_readlane_b32 s61, v255, 19
	v_readlane_b32 s62, v255, 20
	v_readlane_b32 s63, v255, 21
	v_readlane_b32 s64, v255, 22
	v_readlane_b32 s65, v255, 23
	v_readlane_b32 s66, v255, 24
	v_readlane_b32 s67, v255, 25
	s_waitcnt vmcnt(1)
	v_pk_mul_f32 v[36:37], v[28:29], v[34:35] op_sel_hi:[1,0]
	v_pk_mul_f32 v[34:35], v[30:31], v[34:35] op_sel_hi:[1,0]
	ds_write2_b32 v33, v36, v37 offset1:1
	ds_write2_b32 v33, v34, v35 offset0:2 offset1:3
	s_cbranch_execnz .LBB0_316

; #define LAS __attribute__((address_space(3)))
; __device__ __forceinline__ void p0_transpose_item64(const WsRef& wsr, const float* W, int K, int N, bf16* WT, LAS float* scr, int item, int lane, const float* kscale = nullptr) {
;     ...
;     for (int i = 0; i < 16; ++i) { const int kk = 4 * i + kq; const float sc = kscale ? kscale[k0 + kk] : 1.0f; LAS float* d = scr + kk * 65 + nq * 4;
;         d[0] = v[i][0] * sc; d[1] = v[i][1] * sc; d[2] = v[i][2] * sc; d[3] = v[i][3] * sc; }
.LBB0_316:
	s_waitcnt vmcnt(0)
	v_pk_mul_f32 v[24:25], v[24:25], v[32:33] op_sel_hi:[1,0]
	v_add_u32_e32 v28, v87, v105
	ds_write2_b32 v28, v24, v25 offset1:1
	v_pk_mul_f32 v[24:25], v[26:27], v[32:33] op_sel_hi:[1,0]
	s_and_b64 vcc, exec, s[0:1]
	ds_write2_b32 v28, v24, v25 offset0:2 offset1:3
	s_cbranch_vccnz .LBB0_372
	v_readlane_b32 s52, v255, 10
	v_readlane_b32 s58, v255, 16
	v_readlane_b32 s59, v255, 17
	s_nop 4
	global_load_dword v26, v113, s[58:59] offset:160 nt
	global_load_dword v24, v113, s[58:59] offset:176 nt
	v_add_u32_e32 v25, v87, v106
	v_readlane_b32 s53, v255, 11
	v_readlane_b32 s54, v255, 12
	v_readlane_b32 s55, v255, 13
	v_readlane_b32 s56, v255, 14
	v_readlane_b32 s57, v255, 15
	v_readlane_b32 s60, v255, 18
	v_readlane_b32 s61, v255, 19
	v_readlane_b32 s62, v255, 20
	v_readlane_b32 s63, v255, 21
	v_readlane_b32 s64, v255, 22
	v_readlane_b32 s65, v255, 23
	v_readlane_b32 s66, v255, 24
	v_readlane_b32 s67, v255, 25
	s_waitcnt vmcnt(1)
	v_pk_mul_f32 v[28:29], v[20:21], v[26:27] op_sel_hi:[1,0]
	v_pk_mul_f32 v[26:27], v[22:23], v[26:27] op_sel_hi:[1,0]
	ds_write2_b32 v25, v28, v29 offset1:1
	ds_write2_b32 v25, v26, v27 offset0:2 offset1:3
	s_cbranch_execnz .LBB0_319

; #define LAS __attribute__((address_space(3)))
; __device__ __forceinline__ void p0_transpose_item64(const WsRef& wsr, const float* W, int K, int N, bf16* WT, LAS float* scr, int item, int lane, const float* kscale = nullptr) {
;     ...
;     for (int i = 0; i < 16; ++i) { const int kk = 4 * i + kq; const float sc = kscale ? kscale[k0 + kk] : 1.0f; LAS float* d = scr + kk * 65 + nq * 4;
;         d[0] = v[i][0] * sc; d[1] = v[i][1] * sc; d[2] = v[i][2] * sc; d[3] = v[i][3] * sc; }
.LBB0_319:
	s_waitcnt vmcnt(0)
	v_pk_mul_f32 v[20:21], v[16:17], v[24:25] op_sel_hi:[1,0]
	v_add_u32_e32 v17, v87, v106
	v_add_u32_e32 v16, 0x410, v17
	ds_write2_b32 v16, v20, v21 offset1:1
	v_pk_mul_f32 v[18:19], v[18:19], v[24:25] op_sel_hi:[1,0]
	v_add_u32_e32 v16, 0x418, v17
	ds_write2_b32 v16, v18, v19 offset1:1
	s_and_b64 vcc, exec, s[0:1]
	v_add_u32_e32 v18, 0x820, v17
	v_add_u32_e32 v19, 0x828, v17
	s_cbranch_vccnz .LBB0_373
	v_readlane_b32 s52, v255, 10
	v_readlane_b32 s58, v255, 16
	v_readlane_b32 s59, v255, 17
	s_nop 4
	global_load_dword v20, v113, s[58:59] offset:192 nt
	global_load_dword v16, v113, s[58:59] offset:208 nt
	v_readlane_b32 s53, v255, 11
	v_readlane_b32 s54, v255, 12
	v_readlane_b32 s55, v255, 13
	v_readlane_b32 s56, v255, 14
	v_readlane_b32 s57, v255, 15
	v_readlane_b32 s60, v255, 18
	v_readlane_b32 s61, v255, 19
	v_readlane_b32 s62, v255, 20
	v_readlane_b32 s63, v255, 21
	v_readlane_b32 s64, v255, 22
	v_readlane_b32 s65, v255, 23
	v_readlane_b32 s66, v255, 24
	v_readlane_b32 s67, v255, 25
	s_waitcnt vmcnt(1)
	v_pk_mul_f32 v[22:23], v[12:13], v[20:21] op_sel_hi:[1,0]
	v_pk_mul_f32 v[20:21], v[14:15], v[20:21] op_sel_hi:[1,0]
	ds_write2_b32 v18, v22, v23 offset1:1
	ds_write2_b32 v19, v20, v21 offset1:1
	s_cbranch_execnz .LBB0_322

; #define LAS __attribute__((address_space(3)))
; __device__ __forceinline__ void p0_transpose_item64(const WsRef& wsr, const float* W, int K, int N, bf16* WT, LAS float* scr, int item, int lane, const float* kscale = nullptr) {
;     ...
;     for (int i = 0; i < 16; ++i) { const int kk = 4 * i + kq; const float sc = kscale ? kscale[k0 + kk] : 1.0f; LAS float* d = scr + kk * 65 + nq * 4;
;         d[0] = v[i][0] * sc; d[1] = v[i][1] * sc; d[2] = v[i][2] * sc; d[3] = v[i][3] * sc; }
.LBB0_322:
	s_waitcnt vmcnt(0)
	v_pk_mul_f32 v[8:9], v[8:9], v[16:17] op_sel_hi:[1,0]
	v_add_u32_e32 v12, 0xc30, v17
	ds_write2_b32 v12, v8, v9 offset1:1
	v_pk_mul_f32 v[8:9], v[10:11], v[16:17] op_sel_hi:[1,0]
	v_add_u32_e32 v10, 0xc38, v17
	ds_write2_b32 v10, v8, v9 offset1:1
	s_and_b64 vcc, exec, s[0:1]
	v_add_u32_e32 v9, 0x1040, v17
	v_add_u32_e32 v10, 0x1048, v17
	s_cbranch_vccnz .LBB0_374
	v_readlane_b32 s52, v255, 10
	v_readlane_b32 s58, v255, 16
	v_readlane_b32 s59, v255, 17
	s_nop 4
	global_load_dword v12, v113, s[58:59] offset:224 nt
	global_load_dword v8, v113, s[58:59] offset:240 nt
	v_readlane_b32 s53, v255, 11
	v_readlane_b32 s54, v255, 12
	v_readlane_b32 s55, v255, 13
	v_readlane_b32 s56, v255, 14
	v_readlane_b32 s57, v255, 15
	v_readlane_b32 s60, v255, 18
	v_readlane_b32 s61, v255, 19
	v_readlane_b32 s62, v255, 20
	v_readlane_b32 s63, v255, 21
	v_readlane_b32 s64, v255, 22
	v_readlane_b32 s65, v255, 23
	v_readlane_b32 s66, v255, 24
	v_readlane_b32 s67, v255, 25
	s_waitcnt vmcnt(1)
	v_pk_mul_f32 v[14:15], v[4:5], v[12:13] op_sel_hi:[1,0]
	v_pk_mul_f32 v[12:13], v[6:7], v[12:13] op_sel_hi:[1,0]
	ds_write2_b32 v9, v14, v15 offset1:1
	ds_write2_b32 v10, v12, v13 offset1:1
	s_cbranch_execnz .LBB0_325

; #define LAS __attribute__((address_space(3)))
; #define LDS_WAIT() asm volatile("s_waitcnt lgkmcnt(0)" ::: "memory")
; __device__ __forceinline__ void p0_transpose_item64(const WsRef& wsr, const float* W, int K, int N, bf16* WT, LAS float* scr, int item, int lane, const float* kscale = nullptr) {
;     ...
;     for (int i = 0; i < 16; ++i) v[i] = *(const f32x4*)(W + (size_t)(k0 + 4 * i + kq) * N + n0 + nq * 4);
; #pragma unroll
;     for (int i = 0; i < 16; ++i) { const int kk = 4 * i + kq; const float sc = kscale ? kscale[k0 + kk] : 1.0f; LAS float* d = scr + kk * 65 + nq * 4;
;         d[0] = v[i][0] * sc; d[1] = v[i][1] * sc; d[2] = v[i][2] * sc; d[3] = v[i][3] * sc; }
;     LDS_WAIT(); asm volatile("" ::: "memory");
; __global__ void __launch_bounds__(512, 2) fwd_mega(Args a) {
;     ...
;                 if (r < I_SQ) { p0_transpose_item64(wsr, a.in[18], D, D, WXO, scr, r, lane); continue; } r -= I_SQ;
.LBB0_327:
	s_andn2_b64 vcc, exec, s[0:1]
	s_cbranch_vccnz .LBB0_329
	s_and_b32 s1, s31, 0x3c0
	s_and_b32 s0, s3, 0x3c0
	v_or_b32_e32 v2, s1, v86
	s_lshl_b32 s8, s0, 2
	v_lshl_add_u64 v[0:1], v[74:75], 0, s[8:9]
	v_lshlrev_b32_e32 v64, 12, v2
	v_lshl_add_u64 v[60:61], v[0:1], 0, v[64:65]
	v_add_co_u32_e32 v4, vcc, 0x4000, v60
	s_mov_b32 s88, s84
	s_nop 0
	v_addc_co_u32_e32 v5, vcc, 0, v61, vcc
	v_add_co_u32_e32 v8, vcc, 0x8000, v60
	global_load_dwordx4 v[0:3], v[60:61], off nt
	s_nop 0
	global_load_dwordx4 v[4:7], v[4:5], off nt
	v_addc_co_u32_e32 v9, vcc, 0, v61, vcc
	v_add_co_u32_e32 v12, vcc, 0xc000, v60
	s_nop 1
	v_addc_co_u32_e32 v13, vcc, 0, v61, vcc
	v_add_co_u32_e32 v16, vcc, 0x10000, v60
	global_load_dwordx4 v[8:11], v[8:9], off nt
	s_nop 0
	global_load_dwordx4 v[12:15], v[12:13], off nt
	v_addc_co_u32_e32 v17, vcc, 0, v61, vcc
	v_add_co_u32_e32 v20, vcc, 0x14000, v60
	s_nop 1
	v_addc_co_u32_e32 v21, vcc, 0, v61, vcc
	v_add_co_u32_e32 v24, vcc, 0x18000, v60
	global_load_dwordx4 v[16:19], v[16:17], off nt
	s_nop 0
	global_load_dwordx4 v[20:23], v[20:21], off nt
	v_addc_co_u32_e32 v25, vcc, 0, v61, vcc
	v_add_co_u32_e32 v28, vcc, 0x1c000, v60
	s_nop 1
	v_addc_co_u32_e32 v29, vcc, 0, v61, vcc
	global_load_dwordx4 v[24:27], v[24:25], off nt
	s_nop 0
	global_load_dwordx4 v[28:31], v[28:29], off nt
	v_add_co_u32_e32 v32, vcc, 0x20000, v60
	s_nop 1
	v_addc_co_u32_e32 v33, vcc, 0, v61, vcc
	v_add_co_u32_e32 v36, vcc, 0x24000, v60
	s_nop 1
	v_addc_co_u32_e32 v37, vcc, 0, v61, vcc
	global_load_dwordx4 v[32:35], v[32:33], off nt
	s_nop 0
	global_load_dwordx4 v[36:39], v[36:37], off nt
	v_add_co_u32_e32 v40, vcc, 0x28000, v60
	s_nop 1
	v_addc_co_u32_e32 v41, vcc, 0, v61, vcc
	v_add_co_u32_e32 v44, vcc, 0x2c000, v60
	s_nop 1
	v_addc_co_u32_e32 v45, vcc, 0, v61, vcc
	global_load_dwordx4 v[40:43], v[40:41], off nt
	s_nop 0
	global_load_dwordx4 v[44:47], v[44:45], off nt
	v_add_co_u32_e32 v48, vcc, 0x30000, v60
	s_nop 1
	v_addc_co_u32_e32 v49, vcc, 0, v61, vcc
	v_add_co_u32_e32 v52, vcc, 0x34000, v60
	s_nop 1
	v_addc_co_u32_e32 v53, vcc, 0, v61, vcc
	global_load_dwordx4 v[48:51], v[48:49], off nt
	s_nop 0
	global_load_dwordx4 v[52:55], v[52:53], off nt
	v_add_co_u32_e32 v56, vcc, 0x38000, v60
	s_nop 1
	v_addc_co_u32_e32 v57, vcc, 0, v61, vcc
	global_load_dwordx4 v[56:59], v[56:57], off nt
	v_add_co_u32_e32 v60, vcc, 0x3c000, v60
	s_nop 1
	v_addc_co_u32_e32 v61, vcc, 0, v61, vcc
	global_load_dwordx4 v[60:63], v[60:61], off nt
	s_waitcnt vmcnt(0)
	ds_write2_b32 v88, v0, v1 offset1:1
	ds_write2_b32 v88, v2, v3 offset0:2 offset1:3
	ds_write2_b32 v73, v4, v5 offset1:1
	ds_write2_b32 v77, v6, v7 offset1:1
	ds_write2_b32 v81, v8, v9 offset1:1
	ds_write2_b32 v85, v10, v11 offset1:1
	ds_write2_b32 v107, v12, v13 offset1:1
	ds_write2_b32 v108, v14, v15 offset1:1
	ds_write2_b32 v109, v16, v17 offset1:1
	ds_write2_b32 v110, v18, v19 offset1:1
	ds_write2_b32 v111, v20, v21 offset1:1
	ds_write2_b32 v112, v22, v23 offset1:1
	v_add_u32_e32 v0, 0x1860, v88
	v_add_u32_e32 v20, 0x400, v69
	v_lshl_add_u32 v21, s1, 1, v76
	ds_write2_b32 v0, v24, v25 offset1:1
	v_add_u32_e32 v0, 0x1868, v88
	ds_write2_b32 v0, v26, v27 offset1:1
	v_add_u32_e32 v0, 0x1c70, v88
	ds_write2_b32 v0, v28, v29 offset1:1
	v_add_u32_e32 v0, 0x1c78, v88
	ds_write2_b32 v0, v30, v31 offset1:1
	v_add_u32_e32 v0, 0x2080, v88
	ds_write2_b32 v0, v32, v33 offset1:1
	v_add_u32_e32 v0, 0x2088, v88
	ds_write2_b32 v0, v34, v35 offset1:1
	v_add_u32_e32 v0, 0x2490, v88
	ds_write2_b32 v0, v36, v37 offset1:1
	v_add_u32_e32 v0, 0x2498, v88
	ds_write2_b32 v0, v38, v39 offset1:1
	v_add_u32_e32 v0, 0x28a0, v88
	ds_write2_b32 v0, v40, v41 offset1:1
	v_add_u32_e32 v0, 0x28a8, v88
	ds_write2_b32 v0, v42, v43 offset1:1
	v_add_u32_e32 v0, 0x2cb0, v88
	ds_write2_b32 v0, v44, v45 offset1:1
	v_add_u32_e32 v0, 0x2cb8, v88
	ds_write2_b32 v0, v46, v47 offset1:1
	v_add_u32_e32 v0, 0x30c0, v88
	ds_write2_b32 v0, v48, v49 offset1:1
	v_add_u32_e32 v0, 0x30c8, v88
	ds_write2_b32 v0, v50, v51 offset1:1
	v_add_u32_e32 v0, 0x34d0, v88
	ds_write2_b32 v0, v52, v53 offset1:1
	v_add_u32_e32 v0, 0x34d8, v88
	ds_write2_b32 v0, v54, v55 offset1:1
	v_add_u32_e32 v0, 0x38e0, v88
	ds_write2_b32 v0, v56, v57 offset1:1
	v_add_u32_e32 v0, 0x38e8, v88
	ds_write2_b32 v0, v58, v59 offset1:1
	v_add_u32_e32 v0, 0x3cf0, v88
	ds_write2_b32 v0, v60, v61 offset1:1
	v_add_u32_e32 v0, 0x3cf8, v88
	ds_write2_b32 v0, v62, v63 offset1:1
	s_waitcnt lgkmcnt(0)
; #define LAS __attribute__((address_space(3)))
; __device__ __forceinline__ unsigned pk2(float lo, float hi) { return pg8::cvt_pk_bf16(lo, hi); }
; __device__ __forceinline__ void wt_store16(const WsRef& w, const void* p, u32x4 v) { __builtin_amdgcn_raw_buffer_store_b128(v, w.r, (unsigned)((const unsigned char*)p - w.base), 0, 16); }
; __device__ __forceinline__ void p0_transpose_item64(const WsRef& wsr, const float* W, int K, int N, bf16* WT, LAS float* scr, int item, int lane, const float* kscale = nullptr) {
;     ...
;     const int c = lane & 7;
; #pragma unroll
;     for (int j = 0; j < 8; ++j) { const int n = (lane >> 3) + 8 * j; const LAS float* s = scr + (8 * c) * 65 + n;
;         u32x4 o; o.x = pk2(s[0 * 65], s[1 * 65]); o.y = pk2(s[2 * 65], s[3 * 65]); o.z = pk2(s[4 * 65], s[5 * 65]); o.w = pk2(s[6 * 65], s[7 * 65]);
;         wt_store16(wsr, WT + (size_t)(n0 + n) * K + k0 + 8 * c, o); }
	ds_read2_b32 v[4:5], v69 offset1:8
	ds_read2_b32 v[6:7], v69 offset0:65 offset1:73
	ds_read2_b32 v[8:9], v69 offset0:130 offset1:138
	ds_read2_b32 v[10:11], v69 offset0:195 offset1:203
	ds_read2_b32 v[12:13], v20 offset0:4 offset1:12
	ds_read2_b32 v[14:15], v20 offset0:69 offset1:77
	ds_read2_b32 v[16:17], v20 offset0:134 offset1:142
	ds_read2_b32 v[18:19], v20 offset0:199 offset1:207
	s_waitcnt lgkmcnt(6)
	v_cvt_pk_bf16_f32 v0, v4, v6
	v_or_b32_e32 v4, s0, v89
	v_lshl_add_u32 v4, v4, 11, v21
	s_waitcnt lgkmcnt(4)
	v_cvt_pk_bf16_f32 v1, v8, v10
	s_waitcnt lgkmcnt(2)
	v_cvt_pk_bf16_f32 v2, v12, v14
	s_waitcnt lgkmcnt(0)
	v_cvt_pk_bf16_f32 v3, v16, v18
	v_subrev_u32_e32 v4, s84, v4
	buffer_store_dwordx4 v[0:3], v4, s[88:91], 0 offen sc1
	v_or_b32_e32 v4, s0, v90
	v_lshl_add_u32 v4, v4, 11, v21
	v_cvt_pk_bf16_f32 v0, v5, v7
	v_cvt_pk_bf16_f32 v1, v9, v11
	v_cvt_pk_bf16_f32 v2, v13, v15
	v_cvt_pk_bf16_f32 v3, v17, v19
	v_subrev_u32_e32 v22, s84, v4
	ds_read2_b32 v[4:5], v69 offset0:16 offset1:24
	ds_read2_b32 v[6:7], v69 offset0:81 offset1:89
	ds_read2_b32 v[8:9], v69 offset0:146 offset1:154
	ds_read2_b32 v[10:11], v69 offset0:211 offset1:219
	ds_read2_b32 v[12:13], v20 offset0:20 offset1:28
	ds_read2_b32 v[14:15], v20 offset0:85 offset1:93
	ds_read2_b32 v[16:17], v20 offset0:150 offset1:158
	ds_read2_b32 v[18:19], v20 offset0:215 offset1:223
	buffer_store_dwordx4 v[0:3], v22, s[88:91], 0 offen sc1
	s_waitcnt lgkmcnt(6)
	s_nop 0
	v_cvt_pk_bf16_f32 v0, v4, v6
	v_or_b32_e32 v4, s0, v91
	v_lshl_add_u32 v4, v4, 11, v21
	s_waitcnt lgkmcnt(4)
	v_cvt_pk_bf16_f32 v1, v8, v10
	s_waitcnt lgkmcnt(2)
	v_cvt_pk_bf16_f32 v2, v12, v14
	s_waitcnt lgkmcnt(0)
	v_cvt_pk_bf16_f32 v3, v16, v18
	v_subrev_u32_e32 v4, s84, v4
	buffer_store_dwordx4 v[0:3], v4, s[88:91], 0 offen sc1
	v_or_b32_e32 v4, s0, v92
	v_lshl_add_u32 v4, v4, 11, v21
	v_cvt_pk_bf16_f32 v0, v5, v7
	v_cvt_pk_bf16_f32 v1, v9, v11
	v_cvt_pk_bf16_f32 v2, v13, v15
	v_cvt_pk_bf16_f32 v3, v17, v19
	v_subrev_u32_e32 v22, s84, v4
	ds_read2_b32 v[4:5], v69 offset0:32 offset1:40
	ds_read2_b32 v[6:7], v69 offset0:97 offset1:105
	ds_read2_b32 v[8:9], v69 offset0:162 offset1:170
	ds_read2_b32 v[10:11], v69 offset0:227 offset1:235
	ds_read2_b32 v[12:13], v20 offset0:36 offset1:44
	ds_read2_b32 v[14:15], v20 offset0:101 offset1:109
	ds_read2_b32 v[16:17], v20 offset0:166 offset1:174
	ds_read2_b32 v[18:19], v20 offset0:231 offset1:239
	buffer_store_dwordx4 v[0:3], v22, s[88:91], 0 offen sc1
	s_waitcnt lgkmcnt(6)
	s_nop 0
	v_cvt_pk_bf16_f32 v0, v4, v6
	v_or_b32_e32 v4, s0, v93
	v_lshl_add_u32 v4, v4, 11, v21
	s_waitcnt lgkmcnt(4)
	v_cvt_pk_bf16_f32 v1, v8, v10
	s_waitcnt lgkmcnt(2)
	v_cvt_pk_bf16_f32 v2, v12, v14
	s_waitcnt lgkmcnt(0)
	v_cvt_pk_bf16_f32 v3, v16, v18
	v_subrev_u32_e32 v4, s84, v4
	buffer_store_dwordx4 v[0:3], v4, s[88:91], 0 offen sc1
	v_or_b32_e32 v4, s0, v94
	v_lshl_add_u32 v4, v4, 11, v21
	v_cvt_pk_bf16_f32 v0, v5, v7
	v_cvt_pk_bf16_f32 v1, v9, v11
	v_cvt_pk_bf16_f32 v2, v13, v15
	v_cvt_pk_bf16_f32 v3, v17, v19
	v_subrev_u32_e32 v22, s84, v4
	ds_read2_b32 v[4:5], v69 offset0:48 offset1:56
	ds_read2_b32 v[6:7], v69 offset0:113 offset1:121
	ds_read2_b32 v[8:9], v69 offset0:178 offset1:186
	ds_read2_b32 v[10:11], v69 offset0:243 offset1:251
	ds_read2_b32 v[12:13], v20 offset0:52 offset1:60
	ds_read2_b32 v[14:15], v20 offset0:117 offset1:125
	ds_read2_b32 v[16:17], v20 offset0:182 offset1:190
	ds_read2_b32 v[18:19], v20 offset0:247 offset1:255
	buffer_store_dwordx4 v[0:3], v22, s[88:91], 0 offen sc1
	s_waitcnt lgkmcnt(6)
	s_nop 0
	v_cvt_pk_bf16_f32 v0, v4, v6
	v_or_b32_e32 v4, s0, v95
	v_lshl_add_u32 v4, v4, 11, v21
	s_waitcnt lgkmcnt(4)
	v_cvt_pk_bf16_f32 v1, v8, v10
	s_waitcnt lgkmcnt(2)
	v_cvt_pk_bf16_f32 v2, v12, v14
	s_waitcnt lgkmcnt(0)
	v_cvt_pk_bf16_f32 v3, v16, v18
	v_subrev_u32_e32 v4, s84, v4
	buffer_store_dwordx4 v[0:3], v4, s[88:91], 0 offen sc1
	v_or_b32_e32 v4, s0, v96
	v_lshl_add_u32 v4, v4, 11, v21
	v_cvt_pk_bf16_f32 v0, v5, v7
	v_cvt_pk_bf16_f32 v1, v9, v11
	v_cvt_pk_bf16_f32 v2, v13, v15
	v_cvt_pk_bf16_f32 v3, v17, v19
	v_subrev_u32_e32 v4, s84, v4
	buffer_store_dwordx4 v[0:3], v4, s[88:91], 0 offen sc1
	s_waitcnt lgkmcnt(0)

; #define LAS __attribute__((address_space(3)))
; __device__ __forceinline__ void p0_transpose_item64(const WsRef& wsr, const float* W, int K, int N, bf16* WT, LAS float* scr, int item, int lane, const float* kscale = nullptr) {
;     ...
;     for (int i = 0; i < 16; ++i) v[i] = *(const f32x4*)(W + (size_t)(k0 + 4 * i + kq) * N + n0 + nq * 4);
; #pragma unroll
;     for (int i = 0; i < 16; ++i) { const int kk = 4 * i + kq; const float sc = kscale ? kscale[k0 + kk] : 1.0f; LAS float* d = scr + kk * 65 + nq * 4;
;         d[0] = v[i][0] * sc; d[1] = v[i][1] * sc; d[2] = v[i][2] * sc; d[3] = v[i][3] * sc; }
; __global__ void __launch_bounds__(512, 2) fwd_mega(Args a) {
;     ...
;                 if (r < I_SQ) { p0_transpose_item64(wsr, a.in[16], D, D, WXQ, scr, r, lane, a.in[14]); continue; } r -= I_SQ;
.LBB0_330:
	s_andn2_b64 vcc, exec, s[0:1]
	s_cbranch_vccnz .LBB0_356
	s_and_b32 s38, s31, 0x3c0
	s_and_b32 s35, s3, 0x3c0
	v_or_b32_e32 v114, s38, v86
	s_lshl_b32 s8, s35, 2
	v_lshl_add_u64 v[0:1], v[78:79], 0, s[8:9]
	v_lshlrev_b32_e32 v64, 12, v114
	v_lshl_add_u64 v[0:1], v[0:1], 0, v[64:65]
	v_add_co_u32_e32 v2, vcc, 0x4000, v0
	v_cndmask_b32_e64 v64, 0, 1, s[26:27]
	s_nop 0
	v_addc_co_u32_e32 v3, vcc, 0, v1, vcc
	global_load_dwordx4 v[60:63], v[0:1], off nt
	global_load_dwordx4 v[56:59], v[2:3], off nt
	v_add_co_u32_e32 v2, vcc, 0x8000, v0
	v_cmp_ne_u32_e64 s[0:1], 1, v64
	s_nop 0
	v_addc_co_u32_e32 v3, vcc, 0, v1, vcc
	v_add_co_u32_e32 v4, vcc, 0xc000, v0
	v_add_lshl_u32 v113, s38, v86, 2
	s_nop 0
	v_addc_co_u32_e32 v5, vcc, 0, v1, vcc
	global_load_dwordx4 v[52:55], v[2:3], off nt
	global_load_dwordx4 v[48:51], v[4:5], off nt
	v_add_co_u32_e32 v2, vcc, 0x10000, v0
	s_nop 1
	v_addc_co_u32_e32 v3, vcc, 0, v1, vcc
	v_add_co_u32_e32 v4, vcc, 0x14000, v0
	s_nop 1
	v_addc_co_u32_e32 v5, vcc, 0, v1, vcc
	global_load_dwordx4 v[44:47], v[2:3], off nt
	global_load_dwordx4 v[40:43], v[4:5], off nt
	v_add_co_u32_e32 v2, vcc, 0x18000, v0
	s_nop 1
	v_addc_co_u32_e32 v3, vcc, 0, v1, vcc
	v_add_co_u32_e32 v4, vcc, 0x1c000, v0
	s_nop 1
	v_addc_co_u32_e32 v5, vcc, 0, v1, vcc
	global_load_dwordx4 v[36:39], v[2:3], off nt
	global_load_dwordx4 v[32:35], v[4:5], off nt
	v_add_co_u32_e32 v2, vcc, 0x20000, v0
	s_nop 1
	v_addc_co_u32_e32 v3, vcc, 0, v1, vcc
	v_add_co_u32_e32 v4, vcc, 0x24000, v0
	s_nop 1
	v_addc_co_u32_e32 v5, vcc, 0, v1, vcc
	global_load_dwordx4 v[28:31], v[2:3], off nt
	global_load_dwordx4 v[24:27], v[4:5], off nt
	v_add_co_u32_e32 v2, vcc, 0x28000, v0
	s_nop 1
	v_addc_co_u32_e32 v3, vcc, 0, v1, vcc
	v_add_co_u32_e32 v4, vcc, 0x2c000, v0
	s_nop 1
	v_addc_co_u32_e32 v5, vcc, 0, v1, vcc
	global_load_dwordx4 v[20:23], v[2:3], off nt
	global_load_dwordx4 v[16:19], v[4:5], off nt
	v_add_co_u32_e32 v2, vcc, 0x30000, v0
	s_nop 1
	v_addc_co_u32_e32 v3, vcc, 0, v1, vcc
	v_add_co_u32_e32 v4, vcc, 0x34000, v0
	s_nop 1
	v_addc_co_u32_e32 v5, vcc, 0, v1, vcc
	global_load_dwordx4 v[12:15], v[2:3], off nt
	global_load_dwordx4 v[8:11], v[4:5], off nt
	v_add_co_u32_e32 v2, vcc, 0x38000, v0
	s_nop 1
	v_addc_co_u32_e32 v3, vcc, 0, v1, vcc
	v_add_co_u32_e32 v0, vcc, 0x3c000, v0
	s_nop 1
	v_addc_co_u32_e32 v1, vcc, 0, v1, vcc
	global_load_dwordx4 v[4:7], v[2:3], off nt
	s_nop 0
	global_load_dwordx4 v[0:3], v[0:1], off nt
	s_andn2_b64 vcc, exec, s[26:27]
	s_cbranch_vccnz .LBB0_359
	v_lshlrev_b32_e32 v64, 2, v114
	global_load_dword v114, v64, s[48:49] nt
	s_nop 0
	global_load_dword v64, v113, s[48:49] offset:16 nt
	s_waitcnt vmcnt(0)
	v_pk_mul_f32 v[116:117], v[60:61], v[114:115] op_sel_hi:[1,0]
	v_pk_mul_f32 v[114:115], v[62:63], v[114:115] op_sel_hi:[1,0]
	ds_write2_b32 v88, v116, v117 offset1:1
	ds_write2_b32 v88, v114, v115 offset0:2 offset1:3
	s_cbranch_execnz .LBB0_334

; #define LAS __attribute__((address_space(3)))
; __device__ __forceinline__ void p0_transpose_item64(const WsRef& wsr, const float* W, int K, int N, bf16* WT, LAS float* scr, int item, int lane, const float* kscale = nullptr) {
;     ...
;     for (int i = 0; i < 16; ++i) { const int kk = 4 * i + kq; const float sc = kscale ? kscale[k0 + kk] : 1.0f; LAS float* d = scr + kk * 65 + nq * 4;
;         d[0] = v[i][0] * sc; d[1] = v[i][1] * sc; d[2] = v[i][2] * sc; d[3] = v[i][3] * sc; }
.LBB0_334:
	s_waitcnt vmcnt(0)
	v_pk_mul_f32 v[56:57], v[56:57], v[64:65] op_sel_hi:[1,0]
	v_add_u32_e32 v60, v87, v97
	ds_write2_b32 v60, v56, v57 offset1:1
	v_pk_mul_f32 v[56:57], v[58:59], v[64:65] op_sel_hi:[1,0]
	ds_write2_b32 v60, v56, v57 offset0:2 offset1:3
	s_and_b64 vcc, exec, s[0:1]
	v_add_u32_e32 v57, v87, v98
	s_cbranch_vccnz .LBB0_360
	global_load_dword v58, v113, s[48:49] offset:32 nt
	global_load_dword v56, v113, s[48:49] offset:48 nt
	s_waitcnt vmcnt(1)
	v_pk_mul_f32 v[60:61], v[52:53], v[58:59] op_sel_hi:[1,0]
	v_pk_mul_f32 v[58:59], v[54:55], v[58:59] op_sel_hi:[1,0]
	ds_write2_b32 v57, v60, v61 offset1:1
	ds_write2_b32 v57, v58, v59 offset0:2 offset1:3
	s_cbranch_execnz .LBB0_337

; #define LAS __attribute__((address_space(3)))
; __device__ __forceinline__ void p0_transpose_item64(const WsRef& wsr, const float* W, int K, int N, bf16* WT, LAS float* scr, int item, int lane, const float* kscale = nullptr) {
;     ...
;     for (int i = 0; i < 16; ++i) { const int kk = 4 * i + kq; const float sc = kscale ? kscale[k0 + kk] : 1.0f; LAS float* d = scr + kk * 65 + nq * 4;
;         d[0] = v[i][0] * sc; d[1] = v[i][1] * sc; d[2] = v[i][2] * sc; d[3] = v[i][3] * sc; }
.LBB0_337:
	s_waitcnt vmcnt(0)
	v_pk_mul_f32 v[48:49], v[48:49], v[56:57] op_sel_hi:[1,0]
	v_add_u32_e32 v52, v87, v99
	ds_write2_b32 v52, v48, v49 offset1:1
	v_pk_mul_f32 v[48:49], v[50:51], v[56:57] op_sel_hi:[1,0]
	ds_write2_b32 v52, v48, v49 offset0:2 offset1:3
	s_and_b64 vcc, exec, s[0:1]
	v_add_u32_e32 v49, v87, v100
	s_cbranch_vccnz .LBB0_361
	global_load_dword v50, v113, s[48:49] offset:64 nt
	global_load_dword v48, v113, s[48:49] offset:80 nt
	s_waitcnt vmcnt(1)
	v_pk_mul_f32 v[52:53], v[44:45], v[50:51] op_sel_hi:[1,0]
	v_pk_mul_f32 v[50:51], v[46:47], v[50:51] op_sel_hi:[1,0]
	ds_write2_b32 v49, v52, v53 offset1:1
	ds_write2_b32 v49, v50, v51 offset0:2 offset1:3
	s_cbranch_execnz .LBB0_340

; #define LAS __attribute__((address_space(3)))
; __device__ __forceinline__ void p0_transpose_item64(const WsRef& wsr, const float* W, int K, int N, bf16* WT, LAS float* scr, int item, int lane, const float* kscale = nullptr) {
;     ...
;     for (int i = 0; i < 16; ++i) { const int kk = 4 * i + kq; const float sc = kscale ? kscale[k0 + kk] : 1.0f; LAS float* d = scr + kk * 65 + nq * 4;
;         d[0] = v[i][0] * sc; d[1] = v[i][1] * sc; d[2] = v[i][2] * sc; d[3] = v[i][3] * sc; }
.LBB0_340:
	s_waitcnt vmcnt(0)
	v_pk_mul_f32 v[40:41], v[40:41], v[48:49] op_sel_hi:[1,0]
	v_add_u32_e32 v44, v87, v101
	ds_write2_b32 v44, v40, v41 offset1:1
	v_pk_mul_f32 v[40:41], v[42:43], v[48:49] op_sel_hi:[1,0]
	ds_write2_b32 v44, v40, v41 offset0:2 offset1:3
	s_and_b64 vcc, exec, s[0:1]
	v_add_u32_e32 v41, v87, v102
	s_cbranch_vccnz .LBB0_362
	global_load_dword v42, v113, s[48:49] offset:96 nt
	global_load_dword v40, v113, s[48:49] offset:112 nt
	s_waitcnt vmcnt(1)
	v_pk_mul_f32 v[44:45], v[36:37], v[42:43] op_sel_hi:[1,0]
	v_pk_mul_f32 v[42:43], v[38:39], v[42:43] op_sel_hi:[1,0]
	ds_write2_b32 v41, v44, v45 offset1:1
	ds_write2_b32 v41, v42, v43 offset0:2 offset1:3
	s_cbranch_execnz .LBB0_343

; #define LAS __attribute__((address_space(3)))
; __device__ __forceinline__ void p0_transpose_item64(const WsRef& wsr, const float* W, int K, int N, bf16* WT, LAS float* scr, int item, int lane, const float* kscale = nullptr) {
;     ...
;     for (int i = 0; i < 16; ++i) { const int kk = 4 * i + kq; const float sc = kscale ? kscale[k0 + kk] : 1.0f; LAS float* d = scr + kk * 65 + nq * 4;
;         d[0] = v[i][0] * sc; d[1] = v[i][1] * sc; d[2] = v[i][2] * sc; d[3] = v[i][3] * sc; }
.LBB0_343:
	s_waitcnt vmcnt(0)
	v_pk_mul_f32 v[32:33], v[32:33], v[40:41] op_sel_hi:[1,0]
	v_add_u32_e32 v36, v87, v103
	ds_write2_b32 v36, v32, v33 offset1:1
	v_pk_mul_f32 v[32:33], v[34:35], v[40:41] op_sel_hi:[1,0]
	ds_write2_b32 v36, v32, v33 offset0:2 offset1:3
	s_and_b64 vcc, exec, s[0:1]
	v_add_u32_e32 v33, v87, v104
	s_cbranch_vccnz .LBB0_363
	global_load_dword v34, v113, s[48:49] offset:128 nt
	global_load_dword v32, v113, s[48:49] offset:144 nt
	s_waitcnt vmcnt(1)
	v_pk_mul_f32 v[36:37], v[28:29], v[34:35] op_sel_hi:[1,0]
	v_pk_mul_f32 v[34:35], v[30:31], v[34:35] op_sel_hi:[1,0]
	ds_write2_b32 v33, v36, v37 offset1:1
	ds_write2_b32 v33, v34, v35 offset0:2 offset1:3
	s_cbranch_execnz .LBB0_346

; #define LAS __attribute__((address_space(3)))
; __device__ __forceinline__ void p0_transpose_item64(const WsRef& wsr, const float* W, int K, int N, bf16* WT, LAS float* scr, int item, int lane, const float* kscale = nullptr) {
;     ...
;     for (int i = 0; i < 16; ++i) { const int kk = 4 * i + kq; const float sc = kscale ? kscale[k0 + kk] : 1.0f; LAS float* d = scr + kk * 65 + nq * 4;
;         d[0] = v[i][0] * sc; d[1] = v[i][1] * sc; d[2] = v[i][2] * sc; d[3] = v[i][3] * sc; }
.LBB0_346:
	s_waitcnt vmcnt(0)
	v_pk_mul_f32 v[24:25], v[24:25], v[32:33] op_sel_hi:[1,0]
	v_add_u32_e32 v28, v87, v105
	ds_write2_b32 v28, v24, v25 offset1:1
	v_pk_mul_f32 v[24:25], v[26:27], v[32:33] op_sel_hi:[1,0]
	ds_write2_b32 v28, v24, v25 offset0:2 offset1:3
	s_and_b64 vcc, exec, s[0:1]
	v_add_u32_e32 v25, v87, v106
	s_cbranch_vccnz .LBB0_364
	global_load_dword v26, v113, s[48:49] offset:160 nt
	global_load_dword v24, v113, s[48:49] offset:176 nt
	s_waitcnt vmcnt(1)
	v_pk_mul_f32 v[28:29], v[20:21], v[26:27] op_sel_hi:[1,0]
	v_pk_mul_f32 v[26:27], v[22:23], v[26:27] op_sel_hi:[1,0]
	ds_write2_b32 v25, v28, v29 offset1:1
	ds_write2_b32 v25, v26, v27 offset0:2 offset1:3
	s_cbranch_execnz .LBB0_349

; #define LAS __attribute__((address_space(3)))
; __device__ __forceinline__ void p0_transpose_item64(const WsRef& wsr, const float* W, int K, int N, bf16* WT, LAS float* scr, int item, int lane, const float* kscale = nullptr) {
;     ...
;     for (int i = 0; i < 16; ++i) { const int kk = 4 * i + kq; const float sc = kscale ? kscale[k0 + kk] : 1.0f; LAS float* d = scr + kk * 65 + nq * 4;
;         d[0] = v[i][0] * sc; d[1] = v[i][1] * sc; d[2] = v[i][2] * sc; d[3] = v[i][3] * sc; }
.LBB0_349:
	s_waitcnt vmcnt(0)
	v_pk_mul_f32 v[16:17], v[16:17], v[24:25] op_sel_hi:[1,0]
	v_add_u32_e32 v20, 0x410, v25
	ds_write2_b32 v20, v16, v17 offset1:1
	v_pk_mul_f32 v[16:17], v[18:19], v[24:25] op_sel_hi:[1,0]
	v_add_u32_e32 v18, 0x418, v25
	ds_write2_b32 v18, v16, v17 offset1:1
	s_and_b64 vcc, exec, s[0:1]
	v_add_u32_e32 v17, 0x820, v25
	v_add_u32_e32 v18, 0x828, v25
	s_cbranch_vccnz .LBB0_365
	global_load_dword v20, v113, s[48:49] offset:192 nt
	global_load_dword v16, v113, s[48:49] offset:208 nt
	s_waitcnt vmcnt(1)
	v_pk_mul_f32 v[22:23], v[12:13], v[20:21] op_sel_hi:[1,0]
	v_pk_mul_f32 v[20:21], v[14:15], v[20:21] op_sel_hi:[1,0]
	ds_write2_b32 v17, v22, v23 offset1:1
	ds_write2_b32 v18, v20, v21 offset1:1
	s_cbranch_execnz .LBB0_352

; #define LAS __attribute__((address_space(3)))
; __device__ __forceinline__ void p0_transpose_item64(const WsRef& wsr, const float* W, int K, int N, bf16* WT, LAS float* scr, int item, int lane, const float* kscale = nullptr) {
;     ...
;     for (int i = 0; i < 16; ++i) { const int kk = 4 * i + kq; const float sc = kscale ? kscale[k0 + kk] : 1.0f; LAS float* d = scr + kk * 65 + nq * 4;
;         d[0] = v[i][0] * sc; d[1] = v[i][1] * sc; d[2] = v[i][2] * sc; d[3] = v[i][3] * sc; }
.LBB0_352:
	s_waitcnt vmcnt(0)
	v_pk_mul_f32 v[8:9], v[8:9], v[16:17] op_sel_hi:[1,0]
	v_add_u32_e32 v12, 0xc30, v25
	ds_write2_b32 v12, v8, v9 offset1:1
	v_pk_mul_f32 v[8:9], v[10:11], v[16:17] op_sel_hi:[1,0]
	v_add_u32_e32 v10, 0xc38, v25
	ds_write2_b32 v10, v8, v9 offset1:1
	s_and_b64 vcc, exec, s[0:1]
	v_add_u32_e32 v9, 0x1040, v25
	v_add_u32_e32 v10, 0x1048, v25
	s_cbranch_vccnz .LBB0_366
	global_load_dword v12, v113, s[48:49] offset:224 nt
	global_load_dword v8, v113, s[48:49] offset:240 nt
	s_waitcnt vmcnt(1)
	v_pk_mul_f32 v[14:15], v[4:5], v[12:13] op_sel_hi:[1,0]
	v_pk_mul_f32 v[12:13], v[6:7], v[12:13] op_sel_hi:[1,0]
	ds_write2_b32 v9, v14, v15 offset1:1
	ds_write2_b32 v10, v12, v13 offset1:1
	s_cbranch_execnz .LBB0_355

; #define LAS __attribute__((address_space(3)))
; #define LDS_WAIT() asm volatile("s_waitcnt lgkmcnt(0)" ::: "memory")
; __device__ __forceinline__ void p0_transpose_item64(const WsRef& wsr, const float* W, int K, int N, bf16* WT, LAS float* scr, int item, int lane, const float* kscale = nullptr) {
;     const int nblk = N / 64, kb = item / nblk, nb = item % nblk, k0 = 64 * kb, n0 = 64 * nb;
;     const int kq = lane >> 4, nq = lane & 15;
;     f32x4 v[16];
; #pragma unroll
;     for (int i = 0; i < 16; ++i) v[i] = *(const f32x4*)(W + (size_t)(k0 + 4 * i + kq) * N + n0 + nq * 4);
; #pragma unroll
;     for (int i = 0; i < 16; ++i) { const int kk = 4 * i + kq; const float sc = kscale ? kscale[k0 + kk] : 1.0f; LAS float* d = scr + kk * 65 + nq * 4;
;         d[0] = v[i][0] * sc; d[1] = v[i][1] * sc; d[2] = v[i][2] * sc; d[3] = v[i][3] * sc; }
;     LDS_WAIT(); asm volatile("" ::: "memory");
; __global__ void __launch_bounds__(512, 2) fwd_mega(Args a) {
;     ...
;                 if (r < I_SQ) { p0_transpose_item64(wsr, a.in[13], D, D, WOUT, scr, r, lane); continue; } r -= I_SQ;
.LBB0_357:
	s_andn2_b64 vcc, exec, s[0:1]
	s_cbranch_vccnz .LBB0_294
	s_ashr_i32 s0, s34, 31
	s_lshr_b32 s0, s0, 28
	s_add_i32 s0, s34, s0
	s_ashr_i32 s8, s0, 4
	s_lshl_b32 s0, s8, 10
	v_lshl_or_b32 v60, s8, 6, v86
	s_sub_i32 s0, s3, s0
	v_or_b32_e32 v2, 4, v60
	v_or_b32_e32 v8, 8, v60
	v_or_b32_e32 v10, 12, v60
	v_or_b32_e32 v16, 16, v60
	v_or_b32_e32 v18, 20, v60
	s_ashr_i32 s1, s0, 31
	v_ashrrev_i32_e32 v61, 31, v60
	v_ashrrev_i32_e32 v3, 31, v2
	v_ashrrev_i32_e32 v9, 31, v8
	v_ashrrev_i32_e32 v11, 31, v10
	v_ashrrev_i32_e32 v17, 31, v16
	v_ashrrev_i32_e32 v19, 31, v18
	v_lshl_add_u64 v[62:63], s[0:1], 2, v[82:83]
	v_lshlrev_b64 v[0:1], 12, v[60:61]
	v_lshlrev_b64 v[2:3], 12, v[2:3]
	v_lshlrev_b64 v[8:9], 12, v[8:9]
	v_lshlrev_b64 v[10:11], 12, v[10:11]
	v_lshlrev_b64 v[16:17], 12, v[16:17]
	v_lshlrev_b64 v[18:19], 12, v[18:19]
	v_or_b32_e32 v24, 24, v60
	v_or_b32_e32 v26, 28, v60
	v_lshl_add_u64 v[0:1], v[62:63], 0, v[0:1]
	v_lshl_add_u64 v[4:5], v[62:63], 0, v[2:3]
	v_lshl_add_u64 v[8:9], v[62:63], 0, v[8:9]
	v_lshl_add_u64 v[12:13], v[62:63], 0, v[10:11]
	v_lshl_add_u64 v[16:17], v[62:63], 0, v[16:17]
	v_lshl_add_u64 v[20:21], v[62:63], 0, v[18:19]
	v_ashrrev_i32_e32 v25, 31, v24
	v_ashrrev_i32_e32 v27, 31, v26
	global_load_dwordx4 v[0:3], v[0:1], off nt
	s_nop 0
	global_load_dwordx4 v[4:7], v[4:5], off nt
	s_nop 0
	global_load_dwordx4 v[8:11], v[8:9], off nt
	s_nop 0
	global_load_dwordx4 v[12:15], v[12:13], off nt
	s_nop 0
	global_load_dwordx4 v[16:19], v[16:17], off nt
	s_nop 0
	global_load_dwordx4 v[20:23], v[20:21], off nt
	v_lshlrev_b64 v[24:25], 12, v[24:25]
	v_lshlrev_b64 v[26:27], 12, v[26:27]
	v_lshl_add_u64 v[24:25], v[62:63], 0, v[24:25]
	v_lshl_add_u64 v[28:29], v[62:63], 0, v[26:27]
	global_load_dwordx4 v[24:27], v[24:25], off nt
	s_nop 0
	global_load_dwordx4 v[28:31], v[28:29], off nt
	v_or_b32_e32 v32, 32, v60
	v_or_b32_e32 v34, 36, v60
	v_ashrrev_i32_e32 v33, 31, v32
	v_ashrrev_i32_e32 v35, 31, v34
	v_lshlrev_b64 v[32:33], 12, v[32:33]
	v_lshlrev_b64 v[34:35], 12, v[34:35]
	v_lshl_add_u64 v[32:33], v[62:63], 0, v[32:33]
	v_lshl_add_u64 v[36:37], v[62:63], 0, v[34:35]
	global_load_dwordx4 v[32:35], v[32:33], off nt
	s_nop 0
	global_load_dwordx4 v[36:39], v[36:37], off nt
	v_or_b32_e32 v40, 40, v60
	v_or_b32_e32 v42, 44, v60
	v_ashrrev_i32_e32 v41, 31, v40
	v_ashrrev_i32_e32 v43, 31, v42
	v_lshlrev_b64 v[40:41], 12, v[40:41]
	v_lshlrev_b64 v[42:43], 12, v[42:43]
	v_lshl_add_u64 v[40:41], v[62:63], 0, v[40:41]
	v_lshl_add_u64 v[44:45], v[62:63], 0, v[42:43]
	v_or_b32_e32 v48, 48, v60
	global_load_dwordx4 v[40:43], v[40:41], off nt
	s_nop 0
	global_load_dwordx4 v[44:47], v[44:45], off nt
	v_ashrrev_i32_e32 v49, 31, v48
	v_lshlrev_b64 v[48:49], 12, v[48:49]
	v_or_b32_e32 v52, 52, v60
	v_lshl_add_u64 v[48:49], v[62:63], 0, v[48:49]
	v_ashrrev_i32_e32 v53, 31, v52
	global_load_dwordx4 v[48:51], v[48:49], off nt
	v_lshlrev_b64 v[52:53], 12, v[52:53]
	v_or_b32_e32 v56, 56, v60
	v_lshl_add_u64 v[52:53], v[62:63], 0, v[52:53]
	v_ashrrev_i32_e32 v57, 31, v56
	global_load_dwordx4 v[52:55], v[52:53], off nt
	v_lshlrev_b64 v[56:57], 12, v[56:57]
	v_or_b32_e32 v60, 60, v60
	v_lshl_add_u64 v[56:57], v[62:63], 0, v[56:57]
	v_ashrrev_i32_e32 v61, 31, v60
	global_load_dwordx4 v[56:59], v[56:57], off nt
	v_lshlrev_b64 v[60:61], 12, v[60:61]
	v_lshl_add_u64 v[60:61], v[62:63], 0, v[60:61]
	global_load_dwordx4 v[60:63], v[60:61], off nt
	s_lshl_b32 s1, s8, 7
	s_mov_b32 s88, s84
	s_waitcnt vmcnt(0)
	ds_write2_b32 v88, v0, v1 offset1:1
	ds_write2_b32 v88, v2, v3 offset0:2 offset1:3
	ds_write2_b32 v73, v4, v5 offset1:1
	ds_write2_b32 v77, v6, v7 offset1:1
	ds_write2_b32 v81, v8, v9 offset1:1
	ds_write2_b32 v85, v10, v11 offset1:1
	ds_write2_b32 v107, v12, v13 offset1:1
	ds_write2_b32 v108, v14, v15 offset1:1
	ds_write2_b32 v109, v16, v17 offset1:1
	ds_write2_b32 v110, v18, v19 offset1:1
	ds_write2_b32 v111, v20, v21 offset1:1
	ds_write2_b32 v112, v22, v23 offset1:1
	v_add_u32_e32 v0, 0x1860, v88
	v_add_u32_e32 v20, 0x400, v69
	ds_write2_b32 v0, v24, v25 offset1:1
	v_add_u32_e32 v0, 0x1868, v88
	ds_write2_b32 v0, v26, v27 offset1:1
	v_add_u32_e32 v0, 0x1c70, v88
	ds_write2_b32 v0, v28, v29 offset1:1
	v_add_u32_e32 v0, 0x1c78, v88
	ds_write2_b32 v0, v30, v31 offset1:1
	v_add_u32_e32 v0, 0x2080, v88
	ds_write2_b32 v0, v32, v33 offset1:1
	v_add_u32_e32 v0, 0x2088, v88
	ds_write2_b32 v0, v34, v35 offset1:1
	v_add_u32_e32 v0, 0x2490, v88
	ds_write2_b32 v0, v36, v37 offset1:1
	v_add_u32_e32 v0, 0x2498, v88
	ds_write2_b32 v0, v38, v39 offset1:1
	v_add_u32_e32 v0, 0x28a0, v88
	ds_write2_b32 v0, v40, v41 offset1:1
	v_add_u32_e32 v0, 0x28a8, v88
	ds_write2_b32 v0, v42, v43 offset1:1
	v_add_u32_e32 v0, 0x2cb0, v88
	ds_write2_b32 v0, v44, v45 offset1:1
	v_add_u32_e32 v0, 0x2cb8, v88
	ds_write2_b32 v0, v46, v47 offset1:1
	v_add_u32_e32 v0, 0x30c0, v88
	ds_write2_b32 v0, v48, v49 offset1:1
	v_add_u32_e32 v0, 0x30c8, v88
	ds_write2_b32 v0, v50, v51 offset1:1
	v_add_u32_e32 v0, 0x34d0, v88
	ds_write2_b32 v0, v52, v53 offset1:1
	v_add_u32_e32 v0, 0x34d8, v88
	ds_write2_b32 v0, v54, v55 offset1:1
	v_add_u32_e32 v0, 0x38e0, v88
	ds_write2_b32 v0, v56, v57 offset1:1
	v_add_u32_e32 v0, 0x38e8, v88
	ds_write2_b32 v0, v58, v59 offset1:1
	v_add_u32_e32 v0, 0x3cf0, v88
	ds_write2_b32 v0, v60, v61 offset1:1
	v_add_u32_e32 v0, 0x3cf8, v88
	ds_write2_b32 v0, v62, v63 offset1:1
	s_waitcnt lgkmcnt(0)
; #define LAS __attribute__((address_space(3)))
; __device__ __forceinline__ unsigned pk2(float lo, float hi) { return pg8::cvt_pk_bf16(lo, hi); }
; __device__ __forceinline__ void wt_store16(const WsRef& w, const void* p, u32x4 v) { __builtin_amdgcn_raw_buffer_store_b128(v, w.r, (unsigned)((const unsigned char*)p - w.base), 0, 16); }
; __device__ __forceinline__ void p0_transpose_item64(const WsRef& wsr, const float* W, int K, int N, bf16* WT, LAS float* scr, int item, int lane, const float* kscale = nullptr) {
;     ...
;     const int c = lane & 7;
; #pragma unroll
;     for (int j = 0; j < 8; ++j) { const int n = (lane >> 3) + 8 * j; const LAS float* s = scr + (8 * c) * 65 + n;
;         u32x4 o; o.x = pk2(s[0 * 65], s[1 * 65]); o.y = pk2(s[2 * 65], s[3 * 65]); o.z = pk2(s[4 * 65], s[5 * 65]); o.w = pk2(s[6 * 65], s[7 * 65]);
;         wt_store16(wsr, WT + (size_t)(n0 + n) * K + k0 + 8 * c, o); }
	ds_read2_b32 v[4:5], v69 offset1:8
	ds_read2_b32 v[6:7], v69 offset0:65 offset1:73
	ds_read2_b32 v[8:9], v69 offset0:130 offset1:138
	ds_read2_b32 v[10:11], v69 offset0:195 offset1:203
	ds_read2_b32 v[12:13], v20 offset0:4 offset1:12
	ds_read2_b32 v[14:15], v20 offset0:69 offset1:77
	ds_read2_b32 v[16:17], v20 offset0:134 offset1:142
	ds_read2_b32 v[18:19], v20 offset0:199 offset1:207
	s_waitcnt lgkmcnt(6)
	v_cvt_pk_bf16_f32 v0, v4, v6
	v_add_lshl_u32 v4, s0, v89, 11
	v_add3_u32 v4, v84, s1, v4
	s_waitcnt lgkmcnt(4)
	v_cvt_pk_bf16_f32 v1, v8, v10
	s_waitcnt lgkmcnt(2)
	v_cvt_pk_bf16_f32 v2, v12, v14
	s_waitcnt lgkmcnt(0)
	v_cvt_pk_bf16_f32 v3, v16, v18
	v_subrev_u32_e32 v21, s84, v4
	buffer_store_dwordx4 v[0:3], v21, s[88:91], 0 offen sc1
	v_add_u32_e32 v22, 0x4000, v21
	s_nop 0
	v_cvt_pk_bf16_f32 v0, v5, v7
	v_cvt_pk_bf16_f32 v1, v9, v11
	v_cvt_pk_bf16_f32 v2, v13, v15
	v_cvt_pk_bf16_f32 v3, v17, v19
	ds_read2_b32 v[4:5], v69 offset0:16 offset1:24
	ds_read2_b32 v[6:7], v69 offset0:81 offset1:89
	ds_read2_b32 v[8:9], v69 offset0:146 offset1:154
	ds_read2_b32 v[10:11], v69 offset0:211 offset1:219
	ds_read2_b32 v[12:13], v20 offset0:20 offset1:28
	ds_read2_b32 v[14:15], v20 offset0:85 offset1:93
	ds_read2_b32 v[16:17], v20 offset0:150 offset1:158
	ds_read2_b32 v[18:19], v20 offset0:215 offset1:223
	buffer_store_dwordx4 v[0:3], v22, s[88:91], 0 offen sc1
	v_add_u32_e32 v22, 0xc000, v21
	s_waitcnt lgkmcnt(6)
	v_cvt_pk_bf16_f32 v0, v4, v6
	s_waitcnt lgkmcnt(4)
	v_cvt_pk_bf16_f32 v1, v8, v10
	s_waitcnt lgkmcnt(2)
	v_cvt_pk_bf16_f32 v2, v12, v14
	s_waitcnt lgkmcnt(0)
	v_cvt_pk_bf16_f32 v3, v16, v18
	v_add_u32_e32 v4, 0x8000, v21
	buffer_store_dwordx4 v[0:3], v4, s[88:91], 0 offen sc1
	s_nop 1
	v_cvt_pk_bf16_f32 v0, v5, v7
	v_cvt_pk_bf16_f32 v1, v9, v11
	v_cvt_pk_bf16_f32 v2, v13, v15
	v_cvt_pk_bf16_f32 v3, v17, v19
	ds_read2_b32 v[4:5], v69 offset0:32 offset1:40
	ds_read2_b32 v[6:7], v69 offset0:97 offset1:105
	ds_read2_b32 v[8:9], v69 offset0:162 offset1:170
	ds_read2_b32 v[10:11], v69 offset0:227 offset1:235
	ds_read2_b32 v[12:13], v20 offset0:36 offset1:44
	ds_read2_b32 v[14:15], v20 offset0:101 offset1:109
	ds_read2_b32 v[16:17], v20 offset0:166 offset1:174
	ds_read2_b32 v[18:19], v20 offset0:231 offset1:239
	buffer_store_dwordx4 v[0:3], v22, s[88:91], 0 offen sc1
	v_add_u32_e32 v22, 0x14000, v21
	s_waitcnt lgkmcnt(6)
	v_cvt_pk_bf16_f32 v0, v4, v6
	s_waitcnt lgkmcnt(4)
	v_cvt_pk_bf16_f32 v1, v8, v10
	s_waitcnt lgkmcnt(2)
	v_cvt_pk_bf16_f32 v2, v12, v14
	s_waitcnt lgkmcnt(0)
	v_cvt_pk_bf16_f32 v3, v16, v18
	v_add_u32_e32 v4, 0x10000, v21
	buffer_store_dwordx4 v[0:3], v4, s[88:91], 0 offen sc1
	s_nop 1
	v_cvt_pk_bf16_f32 v0, v5, v7
	v_cvt_pk_bf16_f32 v1, v9, v11
	v_cvt_pk_bf16_f32 v2, v13, v15
	v_cvt_pk_bf16_f32 v3, v17, v19
	ds_read2_b32 v[4:5], v69 offset0:48 offset1:56
	ds_read2_b32 v[6:7], v69 offset0:113 offset1:121
	ds_read2_b32 v[8:9], v69 offset0:178 offset1:186
	ds_read2_b32 v[10:11], v69 offset0:243 offset1:251
	ds_read2_b32 v[12:13], v20 offset0:52 offset1:60
	ds_read2_b32 v[14:15], v20 offset0:117 offset1:125
	ds_read2_b32 v[16:17], v20 offset0:182 offset1:190
	ds_read2_b32 v[18:19], v20 offset0:247 offset1:255
	buffer_store_dwordx4 v[0:3], v22, s[88:91], 0 offen sc1
	s_waitcnt lgkmcnt(6)
	s_nop 0
	v_cvt_pk_bf16_f32 v0, v4, v6
	s_waitcnt lgkmcnt(4)
	v_cvt_pk_bf16_f32 v1, v8, v10
	s_waitcnt lgkmcnt(2)
	v_cvt_pk_bf16_f32 v2, v12, v14
	s_waitcnt lgkmcnt(0)
	v_cvt_pk_bf16_f32 v3, v16, v18
	v_add_u32_e32 v4, 0x18000, v21
	buffer_store_dwordx4 v[0:3], v4, s[88:91], 0 offen sc1
	v_add_u32_e32 v4, 0x1c000, v21
	s_nop 0
	v_cvt_pk_bf16_f32 v0, v5, v7
	v_cvt_pk_bf16_f32 v1, v9, v11
	v_cvt_pk_bf16_f32 v2, v13, v15
	v_cvt_pk_bf16_f32 v3, v17, v19
	buffer_store_dwordx4 v[0:3], v4, s[88:91], 0 offen sc1
	s_waitcnt lgkmcnt(0)
	s_branch .LBB0_294
